# attention VALU trimmed: per-block uniform range clamp instead of per-lane edge masks, simplified V row addresses, packed f32 mul/add
# baseline (speedup 1.0000x reference)
.Latt_entry:
	s_mov_b64 exec, -1
	v_readlane_b32 s4, v254, 0
	v_readlane_b32 s5, v254, 1
	v_readlane_b32 s6, v254, 42
	v_readlane_b32 s7, v254, 43
	v_readlane_b32 s8, v254, 46
	v_readlane_b32 s10, v254, 53
	v_readfirstlane_b32 s0, v145
	s_movk_i32 s78, 0x90
	s_movk_i32 s79, 0x110
	s_mov_b32 s80, 0x12100
	s_movk_i32 s82, 0x4000
	s_movk_i32 s83, 0x1000
	s_mov_b32 s84, 0xc000
	s_mov_b32 s85, 0x7ffff000
	s_mov_b32 s70, 0x42a00000
	s_mov_b32 s71, 0xf149f2ca
	s_mov_b32 s72, 0x3fb8aa3b
	s_mov_b32 s73, 0x3fb8aa3b
	s_lshr_b32 s0, s0, 6
	s_mul_i32 s1, s0, 0x1200
	s_add_i32 s1, s1, 0x12500
	s_mov_b32 s37, 0
	v_and_b32_e32 v142, 63, v145
	v_and_b32_e32 v160, 15, v145
	v_bfe_u32 v134, v145, 4, 2
	v_lshlrev_b32_e32 v161, 4, v134
	v_lshlrev_b32_e32 v169, 2, v134
	v_and_b32_e32 v135, 7, v145
	v_lshlrev_b32_e32 v162, 4, v135
	v_bfe_u32 v164, v145, 3, 3
	v_mad_u32_u24 v165, v164, s78, v162
	v_add_u32_e32 v165, s1, v165
	v_bfe_u32 v134, v145, 2, 2
	v_add_u32_e32 v134, v134, v169
	v_and_b32_e32 v135, 3, v145
	v_lshlrev_b32_e32 v135, 3, v135
	v_mad_u32_u24 v166, v134, s78, v135
	v_add_u32_e32 v166, s1, v166
	v_xor_b32_e32 v134, 16, v142
	v_lshlrev_b32_e32 v167, 2, v134
	v_xor_b32_e32 v134, 32, v142
	v_lshlrev_b32_e32 v168, 2, v134
	v_sub_u32_e32 v134, v169, v160
	v_cmp_ge_i32_e64 s[54:55], v134, 0
	v_cmp_le_i32_e64 s[62:63], v134, 0
	v_cmp_ge_i32_e64 s[56:57], v134, -1
	v_cmp_le_i32_e64 s[64:65], v134, -1
	v_cmp_ge_i32_e64 s[58:59], v134, -2
	v_cmp_le_i32_e64 s[66:67], v134, -2
	v_cmp_ge_i32_e64 s[60:61], v134, -3
	v_cmp_le_i32_e64 s[68:69], v134, -3
	v_lshrrev_b32_e32 v134, 1, v145
	v_lshrrev_b32_e32 v135, 4, v134
	v_add_u32_e32 v135, v135, v134
	v_and_b32_e32 v136, 1, v145
	v_lshlrev_b32_e32 v137, 7, v136
	v_mad_u32_u24 v170, v135, s79, v137
	v_lshl_add_u32 v171, v134, 2, s80
	v_lshlrev_b32_e32 v135, 11, v134
	v_lshl_add_u32 v172, v136, 6, v135
	s_lshl_b32 s2, s0, 5
	v_add_u32_e32 v134, s2, v160
	v_mad_u32_u24 v149, v134, s78, v161
	v_bfe_u32 v134, v145, 2, 2
	v_add_u32_e32 v134, v134, v169
	v_add_u32_e32 v134, s2, v134
	v_and_b32_e32 v135, 3, v145
	v_lshlrev_b32_e32 v135, 3, v135
	v_mad_u32_u24 v151, v134, s78, v135
	v_add_u32_e32 v151, 0xd800, v151
	s_mul_i32 s2, s0, 48
	v_add_u32_e32 v134, s2, v164
	v_mad_u32_u24 v253, v134, s78, v162
	v_mov_b32_e32 v130, 0
	v_mov_b32_e32 v131, 0
	v_mov_b32_e32 v184, 0
	v_mov_b32_e32 v185, 0
	s_lshr_b32 s2, s10, 3
	s_and_b32 s3, s10, 7
	s_and_b32 s30, s2, 31
	s_lshl_b32 s31, s3, 5
	s_or_b32 s31, s31, s30
	s_lshr_b32 s30, s10, 8
	s_cmp_eq_u32 s8, 0x100
	s_cselect_b32 s2, s31, s2
	s_cselect_b32 s17, s30, s3
	s_lshl_b32 s16, s2, 8
	s_cmp_lt_u32 s2, 0x80
	s_cselect_b32 s12, s82, s83
	s_cselect_b32 s13, 12, 10
	s_cselect_b32 s3, s84, s85
	s_and_b32 s3, s16, s3
	s_sub_i32 s15, s16, s3
	s_lshr_b32 s30, s12, 4
	s_add_i32 s14, s30, -1
	s_lshl_b32 s30, s17, 23
	s_lshl_b32 s3, s3, 7
	s_add_u32 s30, s30, s3
	s_add_u32 s18, s4, s30
	s_addc_u32 s19, s5, 0
	s_add_u32 s20, s18, 0x4000000
	s_addc_u32 s21, s19, 0
	s_add_u32 s22, s18, 0x8000000
	s_addc_u32 s23, s19, 0
	s_lshl_b32 s2, s0, 5
	s_add_i32 s42, s15, s2
	s_mov_b32 s43, 0
	v_add_u32_e32 v134, s42, v160
	v_add_u32_e32 v134, s43, v134
	v_subrev_u32_e32 v135, s15, v134
	v_lshrrev_b32_e32 v136, 4, v135
	v_add_u32_e32 v136, v136, v135
	v_mad_u32_u24 v176, v136, s79, v161
	v_lshl_add_u32 v177, v135, 2, s80
	s_sub_i32 s2, s42, 64
	v_add_u32_e32 v178, s2, v169
	v_and_b32_e32 v135, 3, v134
	v_lshlrev_b32_e32 v135, s13, v135
	v_lshrrev_b32_e32 v136, 2, v134
	v_add_u32_e32 v135, v135, v136
	v_lshl_add_u32 v135, v135, 7, v161
	v_add_u32_e32 v137, 16, v134
	v_and_b32_e32 v135, 3, v137
	v_lshlrev_b32_e32 v135, s13, v135
	v_lshrrev_b32_e32 v136, 2, v137
	v_add_u32_e32 v135, v135, v136
	v_lshl_add_u32 v135, v135, 7, v161
	s_mul_i32 s2, s0, 48
	s_add_i32 s2, s2, s15
	s_add_i32 s2, s2, -64
	v_add_u32_e32 v138, s2, v164
	v_and_b32_e32 v139, 3, v138
	v_lshlrev_b32_e32 v139, s13, v139
	v_bfe_u32 v140, v138, 2, 2
	v_add_u32_e32 v139, v139, v140
	v_lshl_add_u32 v139, v139, 7, v162
	v_ashrrev_i32_e32 v138, 4, v138
	v_med3_i32 v138, v138, 0, s14
	v_lshl_add_u32 v138, v138, 9, v139
	global_load_dwordx4 v[0:3], v138, s[20:21]
	s_mul_i32 s2, s0, 48
	s_add_i32 s2, s2, s15
	s_add_i32 s2, s2, -56
	v_add_u32_e32 v138, s2, v164
	v_and_b32_e32 v139, 3, v138
	v_lshlrev_b32_e32 v139, s13, v139
	v_bfe_u32 v140, v138, 2, 2
	v_add_u32_e32 v139, v139, v140
	v_lshl_add_u32 v139, v139, 7, v162
	v_ashrrev_i32_e32 v138, 4, v138
	v_med3_i32 v138, v138, 0, s14
	v_lshl_add_u32 v138, v138, 9, v139
	global_load_dwordx4 v[4:7], v138, s[20:21]
	s_mul_i32 s2, s0, 48
	s_add_i32 s2, s2, s15
	s_add_i32 s2, s2, -48
	v_add_u32_e32 v138, s2, v164
	v_and_b32_e32 v139, 3, v138
	v_lshlrev_b32_e32 v139, s13, v139
	v_bfe_u32 v140, v138, 2, 2
	v_add_u32_e32 v139, v139, v140
	v_lshl_add_u32 v139, v139, 7, v162
	v_ashrrev_i32_e32 v138, 4, v138
	v_med3_i32 v138, v138, 0, s14
	v_lshl_add_u32 v138, v138, 9, v139
	global_load_dwordx4 v[8:11], v138, s[20:21]
	s_mul_i32 s2, s0, 48
	s_add_i32 s2, s2, s15
	s_add_i32 s2, s2, -40
	v_add_u32_e32 v138, s2, v164
	v_and_b32_e32 v139, 3, v138
	v_lshlrev_b32_e32 v139, s13, v139
	v_bfe_u32 v140, v138, 2, 2
	v_add_u32_e32 v139, v139, v140
	v_lshl_add_u32 v139, v139, 7, v162
	v_ashrrev_i32_e32 v138, 4, v138
	v_med3_i32 v138, v138, 0, s14
	v_lshl_add_u32 v138, v138, 9, v139
	global_load_dwordx4 v[12:15], v138, s[20:21]
	s_mul_i32 s2, s0, 48
	s_add_i32 s2, s2, s15
	s_add_i32 s2, s2, -32
	v_add_u32_e32 v138, s2, v164
	v_and_b32_e32 v139, 3, v138
	v_lshlrev_b32_e32 v139, s13, v139
	v_bfe_u32 v140, v138, 2, 2
	v_add_u32_e32 v139, v139, v140
	v_lshl_add_u32 v139, v139, 7, v162
	v_ashrrev_i32_e32 v138, 4, v138
	v_med3_i32 v138, v138, 0, s14
	v_lshl_add_u32 v138, v138, 9, v139
	global_load_dwordx4 v[16:19], v138, s[20:21]
	s_mul_i32 s2, s0, 48
	s_add_i32 s2, s2, s15
	s_add_i32 s2, s2, -24
	v_add_u32_e32 v138, s2, v164
	v_and_b32_e32 v139, 3, v138
	v_lshlrev_b32_e32 v139, s13, v139
	v_bfe_u32 v140, v138, 2, 2
	v_add_u32_e32 v139, v139, v140
	v_lshl_add_u32 v139, v139, 7, v162
	v_ashrrev_i32_e32 v138, 4, v138
	v_med3_i32 v138, v138, 0, s14
	v_lshl_add_u32 v138, v138, 9, v139
	global_load_dwordx4 v[20:23], v138, s[20:21]
	s_mul_i32 s2, s0, 48
	s_add_i32 s2, s2, s15
	s_add_i32 s2, s2, -64
	v_add_u32_e32 v138, s2, v164
	v_and_b32_e32 v139, 3, v138
	v_lshlrev_b32_e32 v139, s13, v139
	v_bfe_u32 v140, v138, 2, 2
	v_add_u32_e32 v139, v139, v140
	v_lshl_add_u32 v139, v139, 7, v162
	v_ashrrev_i32_e32 v138, 4, v138
	v_med3_i32 v138, v138, 0, s14
	v_lshl_add_u32 v138, v138, 9, v139
	global_load_dwordx4 v[24:27], v138, s[22:23]
	s_mul_i32 s2, s0, 48
	s_add_i32 s2, s2, s15
	s_add_i32 s2, s2, -56
	v_add_u32_e32 v138, s2, v164
	v_and_b32_e32 v139, 3, v138
	v_lshlrev_b32_e32 v139, s13, v139
	v_bfe_u32 v140, v138, 2, 2
	v_add_u32_e32 v139, v139, v140
	v_lshl_add_u32 v139, v139, 7, v162
	v_ashrrev_i32_e32 v138, 4, v138
	v_med3_i32 v138, v138, 0, s14
	v_lshl_add_u32 v138, v138, 9, v139
	global_load_dwordx4 v[28:31], v138, s[22:23]
	s_mul_i32 s2, s0, 48
	s_add_i32 s2, s2, s15
	s_add_i32 s2, s2, -48
	v_add_u32_e32 v138, s2, v164
	v_and_b32_e32 v139, 3, v138
	v_lshlrev_b32_e32 v139, s13, v139
	v_bfe_u32 v140, v138, 2, 2
	v_add_u32_e32 v139, v139, v140
	v_lshl_add_u32 v139, v139, 7, v162
	v_ashrrev_i32_e32 v138, 4, v138
	v_med3_i32 v138, v138, 0, s14
	v_lshl_add_u32 v138, v138, 9, v139
	global_load_dwordx4 v[32:35], v138, s[22:23]
	s_mul_i32 s2, s0, 48
	s_add_i32 s2, s2, s15
	s_add_i32 s2, s2, -40
	v_add_u32_e32 v138, s2, v164
	v_and_b32_e32 v139, 3, v138
	v_lshlrev_b32_e32 v139, s13, v139
	v_bfe_u32 v140, v138, 2, 2
	v_add_u32_e32 v139, v139, v140
	v_lshl_add_u32 v139, v139, 7, v162
	v_ashrrev_i32_e32 v138, 4, v138
	v_med3_i32 v138, v138, 0, s14
	v_lshl_add_u32 v138, v138, 9, v139
	global_load_dwordx4 v[36:39], v138, s[22:23]
	s_mul_i32 s2, s0, 48
	s_add_i32 s2, s2, s15
	s_add_i32 s2, s2, -32
	v_add_u32_e32 v138, s2, v164
	v_and_b32_e32 v139, 3, v138
	v_lshlrev_b32_e32 v139, s13, v139
	v_bfe_u32 v140, v138, 2, 2
	v_add_u32_e32 v139, v139, v140
	v_lshl_add_u32 v139, v139, 7, v162
	v_ashrrev_i32_e32 v138, 4, v138
	v_med3_i32 v138, v138, 0, s14
	v_lshl_add_u32 v138, v138, 9, v139
	global_load_dwordx4 v[40:43], v138, s[22:23]
	s_mul_i32 s2, s0, 48
	s_add_i32 s2, s2, s15
	s_add_i32 s2, s2, -24
	v_add_u32_e32 v138, s2, v164
	v_and_b32_e32 v139, 3, v138
	v_lshlrev_b32_e32 v139, s13, v139
	v_bfe_u32 v140, v138, 2, 2
	v_add_u32_e32 v139, v139, v140
	v_lshl_add_u32 v139, v139, 7, v162
	v_ashrrev_i32_e32 v138, 4, v138
	v_med3_i32 v138, v138, 0, s14
	v_lshl_add_u32 v138, v138, 9, v139
	global_load_dwordx4 v[44:47], v138, s[22:23]
	s_lshl_b32 s2, s0, 5
	s_add_i32 s2, s2, s15
	s_add_i32 s2, s2, 0
	v_add_u32_e32 v138, s2, v164
	v_and_b32_e32 v139, 3, v138
	v_lshlrev_b32_e32 v139, s13, v139
	v_lshrrev_b32_e32 v140, 2, v138
	v_add_u32_e32 v139, v139, v140
	v_lshl_add_u32 v139, v139, 7, v162
	global_load_dwordx4 v[48:51], v139, s[18:19]
	s_lshl_b32 s2, s0, 5
	s_add_i32 s2, s2, s15
	s_add_i32 s2, s2, 8
	v_add_u32_e32 v138, s2, v164
	v_and_b32_e32 v139, 3, v138
	v_lshlrev_b32_e32 v139, s13, v139
	v_lshrrev_b32_e32 v140, 2, v138
	v_add_u32_e32 v139, v139, v140
	v_lshl_add_u32 v139, v139, 7, v162
	global_load_dwordx4 v[52:55], v139, s[18:19]
	s_lshl_b32 s2, s0, 5
	s_add_i32 s2, s2, s15
	s_add_i32 s2, s2, 16
	v_add_u32_e32 v138, s2, v164
	v_and_b32_e32 v139, 3, v138
	v_lshlrev_b32_e32 v139, s13, v139
	v_lshrrev_b32_e32 v140, 2, v138
	v_add_u32_e32 v139, v139, v140
	v_lshl_add_u32 v139, v139, 7, v162
	global_load_dwordx4 v[56:59], v139, s[18:19]
	s_lshl_b32 s2, s0, 5
	s_add_i32 s2, s2, s15
	s_add_i32 s2, s2, 24
	v_add_u32_e32 v138, s2, v164
	v_and_b32_e32 v139, 3, v138
	v_lshlrev_b32_e32 v139, s13, v139
	v_lshrrev_b32_e32 v140, 2, v138
	v_add_u32_e32 v139, v139, v140
	v_lshl_add_u32 v139, v139, 7, v162
	global_load_dwordx4 v[60:63], v139, s[18:19]
	s_waitcnt vmcnt(0)
.Latt_unit:
	s_mov_b32 s33, s12
	s_mov_b32 s34, s15
	s_mov_b32 s35, s16
	s_mov_b32 s36, s17
	s_mov_b32 s38, s14
	s_mov_b32 s39, s13
	s_mov_b32 s24, s20
	s_mov_b32 s25, s21
	s_mov_b32 s26, s22
	s_mov_b32 s27, s23
	s_mov_b32 s40, s42
	s_mov_b32 s41, s43
	v_mov_b32_e32 v173, v176
	v_mov_b32_e32 v174, v177
	v_mov_b32_e32 v175, v178
	v_mov_b32_e32 v179, v183
	v_mov_b32_e32 v182, v252
	s_lshr_b32 s44, s33, 0
	s_lshr_b32 s2, s0, 2
	s_lshl_b32 s2, s2, 5
	s_lshr_b32 s3, s15, 2
	s_add_i32 s42, s3, s2
	s_and_b32 s43, s0, 3
	s_waitcnt vmcnt(4)
	ds_write_b128 v253, v[0:3]
	ds_write_b128 v253, v[4:7] offset:1152
	ds_write_b128 v253, v[8:11] offset:2304
	ds_write_b128 v253, v[12:15] offset:3456
	ds_write_b128 v253, v[16:19] offset:4608
	ds_write_b128 v253, v[20:23] offset:5760
	ds_write_b128 v253, v[24:27] offset:55296
	ds_write_b128 v253, v[28:31] offset:56448
	ds_write_b128 v253, v[32:35] offset:57600
	ds_write_b128 v253, v[36:39] offset:58752
	ds_write_b128 v253, v[40:43] offset:59904
	ds_write_b128 v253, v[44:47] offset:61056
	s_lshl_b32 s2, s0, 12
	s_add_i32 s2, s2, 0x1b500
	v_and_b32_e32 v141, 63, v145
	v_lshl_add_u32 v141, v141, 4, s2
	ds_write_b128 v141, v[48:51]
	ds_write_b128 v141, v[52:55] offset:1024
	ds_write_b128 v141, v[56:59] offset:2048
	ds_write_b128 v141, v[60:63] offset:3072
	s_waitcnt lgkmcnt(0)
	s_barrier
	v_add_u32_e32 v134, s42, v160
	v_lshlrev_b32_e32 v134, 2, v134
	v_add_u32_e32 v134, s43, v134
	v_subrev_u32_e32 v135, s15, v134
	v_lshrrev_b32_e32 v136, 4, v135
	v_add_u32_e32 v136, v136, v135
	v_mad_u32_u24 v176, v136, s79, v161
	v_lshl_add_u32 v177, v135, 2, s80
	s_sub_i32 s2, s42, 64
	v_add_u32_e32 v178, s2, v169
	v_subrev_u32_e32 v134, 0x100, v134
	v_and_b32_e32 v137, 3, v134
	v_lshlrev_b32_e32 v137, s13, v137
	v_bfe_u32 v135, v134, 2, 2
	v_add_u32_e32 v137, v137, v135
	v_lshl_add_u32 v183, v137, 7, v161
	v_ashrrev_i32_e32 v252, 4, v134
	v_med3_i32 v136, v252, 0, s14
	v_lshl_add_u32 v136, v136, 9, v183
	global_load_dwordx4 v[0:3], v136, s[20:21]
	global_load_dwordx4 v[4:7], v136, s[20:21] offset:64
	v_add_u32_e32 v135, 4, v252
	v_med3_i32 v135, v135, 0, s14
	v_lshl_add_u32 v135, v135, 9, v183
	global_load_dwordx4 v[8:11], v135, s[20:21]
	global_load_dwordx4 v[12:15], v135, s[20:21] offset:64
	v_add_u32_e32 v136, 8, v252
	v_med3_i32 v136, v136, 0, s14
	v_lshl_add_u32 v136, v136, 9, v183
	global_load_dwordx4 v[16:19], v136, s[20:21]
	global_load_dwordx4 v[20:23], v136, s[20:21] offset:64
	v_add_u32_e32 v135, 12, v252
	v_med3_i32 v135, v135, 0, s14
	v_lshl_add_u32 v135, v135, 9, v183
	global_load_dwordx4 v[24:27], v135, s[20:21]
	global_load_dwordx4 v[28:31], v135, s[20:21] offset:64
	v_add_u32_e32 v136, 16, v252
	v_med3_i32 v136, v136, 0, s14
	v_lshl_add_u32 v136, v136, 9, v183
	global_load_dwordx4 v[32:35], v136, s[20:21]
	global_load_dwordx4 v[36:39], v136, s[20:21] offset:64
	v_add_u32_e32 v135, 20, v252
	v_med3_i32 v135, v135, 0, s14
	v_lshl_add_u32 v135, v135, 9, v183
	global_load_dwordx4 v[40:43], v135, s[20:21]
	global_load_dwordx4 v[44:47], v135, s[20:21] offset:64
	s_lshl_b32 s2, s43, s13
	s_lshl_b32 s2, s2, 7
	s_add_u32 s74, s22, s2
	s_addc_u32 s75, s23, 0
	v_and_b32_e32 v139, 3, v164
	v_lshl_add_u32 v139, v139, 7, v162
	s_add_i32 s2, s42, -64
	v_add_u32_e32 v138, s2, v164
	v_ashrrev_i32_e32 v138, 2, v138
	v_med3_i32 v138, v138, 0, s14
	v_lshl_add_u32 v138, v138, 9, v139
	global_load_dwordx4 v[64:67], v138, s[74:75]
	s_add_i32 s2, s42, -56
	v_add_u32_e32 v138, s2, v164
	v_ashrrev_i32_e32 v138, 2, v138
	v_med3_i32 v138, v138, 0, s14
	v_lshl_add_u32 v138, v138, 9, v139
	global_load_dwordx4 v[68:71], v138, s[74:75]
	s_add_i32 s2, s42, -48
	v_add_u32_e32 v138, s2, v164
	v_ashrrev_i32_e32 v138, 2, v138
	v_med3_i32 v138, v138, 0, s14
	v_lshl_add_u32 v138, v138, 9, v139
	global_load_dwordx4 v[72:75], v138, s[74:75]
	s_add_i32 s2, s42, -40
	v_add_u32_e32 v138, s2, v164
	v_ashrrev_i32_e32 v138, 2, v138
	v_med3_i32 v138, v138, 0, s14
	v_lshl_add_u32 v138, v138, 9, v139
	global_load_dwordx4 v[76:79], v138, s[74:75]
	s_lshl_b32 s2, s43, s13
	s_lshl_b32 s2, s2, 7
	s_add_u32 s74, s22, s2
	s_addc_u32 s75, s23, 0
	v_and_b32_e32 v139, 3, v164
	v_lshl_add_u32 v139, v139, 7, v162
	s_add_i32 s2, s42, -32
	v_add_u32_e32 v138, s2, v164
	v_ashrrev_i32_e32 v138, 2, v138
	v_med3_i32 v138, v138, 0, s14
	v_lshl_add_u32 v138, v138, 9, v139
	global_load_dwordx4 v[80:83], v138, s[74:75]
	s_add_i32 s2, s42, -24
	v_add_u32_e32 v138, s2, v164
	v_ashrrev_i32_e32 v138, 2, v138
	v_med3_i32 v138, v138, 0, s14
	v_lshl_add_u32 v138, v138, 9, v139
	global_load_dwordx4 v[84:87], v138, s[74:75]
	s_add_i32 s2, s42, -16
	v_add_u32_e32 v138, s2, v164
	v_ashrrev_i32_e32 v138, 2, v138
	v_med3_i32 v138, v138, 0, s14
	v_lshl_add_u32 v138, v138, 9, v139
	global_load_dwordx4 v[88:91], v138, s[74:75]
	s_add_i32 s2, s42, -8
	v_add_u32_e32 v138, s2, v164
	v_ashrrev_i32_e32 v138, 2, v138
	v_med3_i32 v138, v138, 0, s14
	v_lshl_add_u32 v138, v138, 9, v139
	global_load_dwordx4 v[92:95], v138, s[74:75]
	s_lshl_b32 s2, s43, s13
	s_lshl_b32 s2, s2, 7
	s_add_u32 s74, s22, s2
	s_addc_u32 s75, s23, 0
	v_and_b32_e32 v139, 3, v164
	v_lshl_add_u32 v139, v139, 7, v162
	s_add_i32 s2, s42, 0
	v_add_u32_e32 v138, s2, v164
	v_ashrrev_i32_e32 v138, 2, v138
	v_med3_i32 v138, v138, 0, s14
	v_lshl_add_u32 v138, v138, 9, v139
	global_load_dwordx4 v[96:99], v138, s[74:75]
	s_add_i32 s2, s42, 8
	v_add_u32_e32 v138, s2, v164
	v_ashrrev_i32_e32 v138, 2, v138
	v_med3_i32 v138, v138, 0, s14
	v_lshl_add_u32 v138, v138, 9, v139
	global_load_dwordx4 v[100:103], v138, s[74:75]
	s_add_i32 s2, s42, 16
	v_add_u32_e32 v138, s2, v164
	v_ashrrev_i32_e32 v138, 2, v138
	v_med3_i32 v138, v138, 0, s14
	v_lshl_add_u32 v138, v138, 9, v139
	global_load_dwordx4 v[104:107], v138, s[74:75]
	s_add_i32 s2, s42, 24
	v_add_u32_e32 v138, s2, v164
	v_ashrrev_i32_e32 v138, 2, v138
	v_med3_i32 v138, v138, 0, s14
	v_lshl_add_u32 v138, v138, 9, v139
	global_load_dwordx4 v[108:111], v138, s[74:75]
	v_subrev_u32_e32 v143, s80, v174
	v_lshl_add_u32 v143, v143, 5, v161
	v_add_u32_e32 v143, 0x1b500, v143
	ds_read_b128 v[48:51], v143
	ds_read_b128 v[52:55], v143 offset:64
	ds_read_b128 v[56:59], v143 offset:2048
	ds_read_b128 v[60:63], v143 offset:2112
	s_waitcnt lgkmcnt(0)
	v_mov_b32_e32 v138, 0
	v_mov_b32_e32 v139, 0
	v_mov_b32_e32 v140, 0
	v_mov_b32_e32 v141, 0
	ds_read_b128 v[204:207], v149
	ds_read_b128 v[208:211], v149 offset:64
	ds_read_b128 v[212:215], v149 offset:2304
	ds_read_b128 v[216:219], v149 offset:2368
	ds_read_b128 v[220:223], v149 offset:4608
	ds_read_b128 v[224:227], v149 offset:4672
	ds_read_b128 v[228:231], v149 offset:6912
	ds_read_b128 v[232:235], v149 offset:6976
	s_waitcnt lgkmcnt(0)
	v_mfma_f32_16x16x32_bf16 v[236:239], v[204:207], v[48:51], 0
	v_mfma_f32_16x16x32_bf16 v[236:239], v[208:211], v[52:55], v[236:239]
	v_mfma_f32_16x16x32_bf16 v[240:243], v[212:215], v[48:51], 0
	v_mfma_f32_16x16x32_bf16 v[240:243], v[216:219], v[52:55], v[240:243]
	v_mfma_f32_16x16x32_bf16 v[248:251], v[212:215], v[56:59], 0
	v_mfma_f32_16x16x32_bf16 v[248:251], v[216:219], v[60:63], v[248:251]
	s_nop 7
	s_add_i32 s77, s40, -64
	s_cmp_lt_u32 s77, s44
	s_cselect_b32 s76, s70, s71
	v_min_f32_e32 v152, s76, v236
	v_min_f32_e32 v153, s76, v237
	v_min_f32_e32 v154, s76, v238
	v_min_f32_e32 v155, s76, v239
	v_mfma_f32_16x16x32_bf16 v[236:239], v[220:223], v[48:51], 0
	v_mfma_f32_16x16x32_bf16 v[236:239], v[224:227], v[52:55], v[236:239]
	v_mfma_f32_16x16x32_bf16 v[244:247], v[220:223], v[56:59], 0
	v_mfma_f32_16x16x32_bf16 v[244:247], v[224:227], v[60:63], v[244:247]
	ds_read_b128 v[204:207], v149 offset:9216
	ds_read_b128 v[208:211], v149 offset:9280
	v_pk_mul_f32 v[152:153], v[152:153], s[72:73]
	v_pk_mul_f32 v[154:155], v[154:155], s[72:73]
	v_exp_f32_e32 v152, v152
	v_exp_f32_e32 v153, v153
	v_exp_f32_e32 v154, v154
	v_exp_f32_e32 v155, v155
	v_cndmask_b32_e64 v152, 0, v152, s[54:55]
	v_cndmask_b32_e64 v153, 0, v153, s[56:57]
	v_cndmask_b32_e64 v154, 0, v154, s[58:59]
	v_cndmask_b32_e64 v155, 0, v155, s[60:61]
	v_pk_add_f32 v[138:139], v[138:139], v[152:153]
	v_pk_add_f32 v[138:139], v[138:139], v[154:155]
	v_cvt_pk_bf16_f32 v112, v152, v153
	v_cvt_pk_bf16_f32 v113, v154, v155
	s_add_i32 s77, s40, -48
	s_cmp_lt_u32 s77, s44
	s_cselect_b32 s76, s70, s71
	v_min_f32_e32 v152, s76, v240
	v_min_f32_e32 v153, s76, v241
	v_min_f32_e32 v154, s76, v242
	v_min_f32_e32 v155, s76, v243
	v_min_f32_e32 v156, s76, v248
	v_min_f32_e32 v157, s76, v249
	v_min_f32_e32 v158, s76, v250
	v_min_f32_e32 v159, s76, v251
	v_mfma_f32_16x16x32_bf16 v[240:243], v[228:231], v[48:51], 0
	v_mfma_f32_16x16x32_bf16 v[240:243], v[232:235], v[52:55], v[240:243]
	v_mfma_f32_16x16x32_bf16 v[248:251], v[228:231], v[56:59], 0
	v_mfma_f32_16x16x32_bf16 v[248:251], v[232:235], v[60:63], v[248:251]
	ds_read_b128 v[212:215], v149 offset:11520
	ds_read_b128 v[216:219], v149 offset:11584
	v_pk_mul_f32 v[152:153], v[152:153], s[72:73]
	v_pk_mul_f32 v[154:155], v[154:155], s[72:73]
	v_exp_f32_e32 v152, v152
	v_exp_f32_e32 v153, v153
	v_exp_f32_e32 v154, v154
	v_exp_f32_e32 v155, v155
	v_pk_add_f32 v[138:139], v[138:139], v[152:153]
	v_pk_add_f32 v[138:139], v[138:139], v[154:155]
	v_cvt_pk_bf16_f32 v114, v152, v153
	v_cvt_pk_bf16_f32 v115, v154, v155
	v_pk_mul_f32 v[156:157], v[156:157], s[72:73]
	v_pk_mul_f32 v[158:159], v[158:159], s[72:73]
	v_exp_f32_e32 v156, v156
	v_exp_f32_e32 v157, v157
	v_exp_f32_e32 v158, v158
	v_exp_f32_e32 v159, v159
	v_cndmask_b32_e64 v156, 0, v156, s[54:55]
	v_cndmask_b32_e64 v157, 0, v157, s[56:57]
	v_cndmask_b32_e64 v158, 0, v158, s[58:59]
	v_cndmask_b32_e64 v159, 0, v159, s[60:61]
	v_pk_add_f32 v[140:141], v[140:141], v[156:157]
	v_pk_add_f32 v[140:141], v[140:141], v[158:159]
	v_cvt_pk_bf16_f32 v186, v156, v157
	v_cvt_pk_bf16_f32 v187, v158, v159
	s_add_i32 s77, s40, -32
	s_cmp_lt_u32 s77, s44
	s_cselect_b32 s76, s70, s71
	v_min_f32_e32 v152, s76, v236
	v_min_f32_e32 v153, s76, v237
	v_min_f32_e32 v154, s76, v238
	v_min_f32_e32 v155, s76, v239
	v_min_f32_e32 v156, s76, v244
	v_min_f32_e32 v157, s76, v245
	v_min_f32_e32 v158, s76, v246
	v_min_f32_e32 v159, s76, v247
	s_waitcnt lgkmcnt(2)
	v_mfma_f32_16x16x32_bf16 v[236:239], v[204:207], v[48:51], 0
	v_mfma_f32_16x16x32_bf16 v[236:239], v[208:211], v[52:55], v[236:239]
	v_mfma_f32_16x16x32_bf16 v[244:247], v[204:207], v[56:59], 0
	v_mfma_f32_16x16x32_bf16 v[244:247], v[208:211], v[60:63], v[244:247]
	ds_read_b128 v[220:223], v149 offset:13824
	ds_read_b128 v[224:227], v149 offset:13888
	v_pk_mul_f32 v[152:153], v[152:153], s[72:73]
	v_pk_mul_f32 v[154:155], v[154:155], s[72:73]
	v_exp_f32_e32 v152, v152
	v_exp_f32_e32 v153, v153
	v_exp_f32_e32 v154, v154
	v_exp_f32_e32 v155, v155
	v_pk_add_f32 v[138:139], v[138:139], v[152:153]
	v_pk_add_f32 v[138:139], v[138:139], v[154:155]
	v_cvt_pk_bf16_f32 v116, v152, v153
	v_cvt_pk_bf16_f32 v117, v154, v155
	v_pk_mul_f32 v[156:157], v[156:157], s[72:73]
	v_pk_mul_f32 v[158:159], v[158:159], s[72:73]
	v_exp_f32_e32 v156, v156
	v_exp_f32_e32 v157, v157
	v_exp_f32_e32 v158, v158
	v_exp_f32_e32 v159, v159
	v_pk_add_f32 v[140:141], v[140:141], v[156:157]
	v_pk_add_f32 v[140:141], v[140:141], v[158:159]
	v_cvt_pk_bf16_f32 v188, v156, v157
	v_cvt_pk_bf16_f32 v189, v158, v159
	s_add_i32 s77, s40, -16
	s_cmp_lt_u32 s77, s44
	s_cselect_b32 s76, s70, s71
	v_min_f32_e32 v152, s76, v240
	v_min_f32_e32 v153, s76, v241
	v_min_f32_e32 v154, s76, v242
	v_min_f32_e32 v155, s76, v243
	v_min_f32_e32 v156, s76, v248
	v_min_f32_e32 v157, s76, v249
	v_min_f32_e32 v158, s76, v250
	v_min_f32_e32 v159, s76, v251
	s_waitcnt lgkmcnt(2)
	v_mfma_f32_16x16x32_bf16 v[240:243], v[212:215], v[48:51], 0
	v_mfma_f32_16x16x32_bf16 v[240:243], v[216:219], v[52:55], v[240:243]
	v_mfma_f32_16x16x32_bf16 v[248:251], v[212:215], v[56:59], 0
	v_mfma_f32_16x16x32_bf16 v[248:251], v[216:219], v[60:63], v[248:251]
	ds_read_b128 v[228:231], v149 offset:16128
	ds_read_b128 v[232:235], v149 offset:16192
	v_pk_mul_f32 v[152:153], v[152:153], s[72:73]
	v_pk_mul_f32 v[154:155], v[154:155], s[72:73]
	v_exp_f32_e32 v152, v152
	v_exp_f32_e32 v153, v153
	v_exp_f32_e32 v154, v154
	v_exp_f32_e32 v155, v155
	v_pk_add_f32 v[138:139], v[138:139], v[152:153]
	v_pk_add_f32 v[138:139], v[138:139], v[154:155]
	v_cvt_pk_bf16_f32 v118, v152, v153
	v_cvt_pk_bf16_f32 v119, v154, v155
	v_pk_mul_f32 v[156:157], v[156:157], s[72:73]
	v_pk_mul_f32 v[158:159], v[158:159], s[72:73]
	v_exp_f32_e32 v156, v156
	v_exp_f32_e32 v157, v157
	v_exp_f32_e32 v158, v158
	v_exp_f32_e32 v159, v159
	v_pk_add_f32 v[140:141], v[140:141], v[156:157]
	v_pk_add_f32 v[140:141], v[140:141], v[158:159]
	v_cvt_pk_bf16_f32 v190, v156, v157
	v_cvt_pk_bf16_f32 v191, v158, v159
	s_add_i32 s77, s40, 0
	s_cmp_lt_u32 s77, s44
	s_cselect_b32 s76, s70, s71
	v_min_f32_e32 v152, s76, v236
	v_min_f32_e32 v153, s76, v237
	v_min_f32_e32 v154, s76, v238
	v_min_f32_e32 v155, s76, v239
	v_min_f32_e32 v156, s76, v244
	v_min_f32_e32 v157, s76, v245
	v_min_f32_e32 v158, s76, v246
	v_min_f32_e32 v159, s76, v247
	s_waitcnt lgkmcnt(2)
	v_mfma_f32_16x16x32_bf16 v[236:239], v[220:223], v[48:51], 0
	v_mfma_f32_16x16x32_bf16 v[236:239], v[224:227], v[52:55], v[236:239]
	v_mfma_f32_16x16x32_bf16 v[244:247], v[220:223], v[56:59], 0
	v_mfma_f32_16x16x32_bf16 v[244:247], v[224:227], v[60:63], v[244:247]
	ds_read_b128 v[204:207], v149 offset:18432
	ds_read_b128 v[208:211], v149 offset:18496
	v_pk_mul_f32 v[152:153], v[152:153], s[72:73]
	v_pk_mul_f32 v[154:155], v[154:155], s[72:73]
	v_exp_f32_e32 v152, v152
	v_exp_f32_e32 v153, v153
	v_exp_f32_e32 v154, v154
	v_exp_f32_e32 v155, v155
	v_pk_add_f32 v[138:139], v[138:139], v[152:153]
	v_pk_add_f32 v[138:139], v[138:139], v[154:155]
	v_cvt_pk_bf16_f32 v120, v152, v153
	v_cvt_pk_bf16_f32 v121, v154, v155
	v_pk_mul_f32 v[156:157], v[156:157], s[72:73]
	v_pk_mul_f32 v[158:159], v[158:159], s[72:73]
	v_exp_f32_e32 v156, v156
	v_exp_f32_e32 v157, v157
	v_exp_f32_e32 v158, v158
	v_exp_f32_e32 v159, v159
	v_pk_add_f32 v[140:141], v[140:141], v[156:157]
	v_pk_add_f32 v[140:141], v[140:141], v[158:159]
	v_cvt_pk_bf16_f32 v192, v156, v157
	v_cvt_pk_bf16_f32 v193, v158, v159
	s_add_i32 s77, s40, 16
	s_cmp_lt_u32 s77, s44
	s_cselect_b32 s76, s70, s71
	v_min_f32_e32 v152, s76, v240
	v_min_f32_e32 v153, s76, v241
	v_min_f32_e32 v154, s76, v242
	v_min_f32_e32 v155, s76, v243
	v_min_f32_e32 v156, s76, v248
	v_min_f32_e32 v157, s76, v249
	v_min_f32_e32 v158, s76, v250
	v_min_f32_e32 v159, s76, v251
	s_waitcnt lgkmcnt(2)
	v_mfma_f32_16x16x32_bf16 v[240:243], v[228:231], v[48:51], 0
	v_mfma_f32_16x16x32_bf16 v[240:243], v[232:235], v[52:55], v[240:243]
	v_mfma_f32_16x16x32_bf16 v[248:251], v[228:231], v[56:59], 0
	v_mfma_f32_16x16x32_bf16 v[248:251], v[232:235], v[60:63], v[248:251]
	ds_read_b128 v[212:215], v149 offset:20736
	ds_read_b128 v[216:219], v149 offset:20800
	v_pk_mul_f32 v[152:153], v[152:153], s[72:73]
	v_pk_mul_f32 v[154:155], v[154:155], s[72:73]
	v_exp_f32_e32 v152, v152
	v_exp_f32_e32 v153, v153
	v_exp_f32_e32 v154, v154
	v_exp_f32_e32 v155, v155
	v_pk_add_f32 v[138:139], v[138:139], v[152:153]
	v_pk_add_f32 v[138:139], v[138:139], v[154:155]
	v_cvt_pk_bf16_f32 v122, v152, v153
	v_cvt_pk_bf16_f32 v123, v154, v155
	v_pk_mul_f32 v[156:157], v[156:157], s[72:73]
	v_pk_mul_f32 v[158:159], v[158:159], s[72:73]
	v_exp_f32_e32 v156, v156
	v_exp_f32_e32 v157, v157
	v_exp_f32_e32 v158, v158
	v_exp_f32_e32 v159, v159
	v_pk_add_f32 v[140:141], v[140:141], v[156:157]
	v_pk_add_f32 v[140:141], v[140:141], v[158:159]
	v_cvt_pk_bf16_f32 v194, v156, v157
	v_cvt_pk_bf16_f32 v195, v158, v159
	s_add_i32 s77, s40, 32
	s_cmp_lt_u32 s77, s44
	s_cselect_b32 s76, s70, s71
	v_min_f32_e32 v152, s76, v236
	v_min_f32_e32 v153, s76, v237
	v_min_f32_e32 v154, s76, v238
	v_min_f32_e32 v155, s76, v239
	v_min_f32_e32 v156, s76, v244
	v_min_f32_e32 v157, s76, v245
	v_min_f32_e32 v158, s76, v246
	v_min_f32_e32 v159, s76, v247
	s_waitcnt lgkmcnt(2)
	v_mfma_f32_16x16x32_bf16 v[236:239], v[204:207], v[48:51], 0
	v_mfma_f32_16x16x32_bf16 v[236:239], v[208:211], v[52:55], v[236:239]
	v_mfma_f32_16x16x32_bf16 v[244:247], v[204:207], v[56:59], 0
	v_mfma_f32_16x16x32_bf16 v[244:247], v[208:211], v[60:63], v[244:247]
	v_pk_mul_f32 v[152:153], v[152:153], s[72:73]
	v_pk_mul_f32 v[154:155], v[154:155], s[72:73]
	v_exp_f32_e32 v152, v152
	v_exp_f32_e32 v153, v153
	v_exp_f32_e32 v154, v154
	v_exp_f32_e32 v155, v155
	v_pk_add_f32 v[138:139], v[138:139], v[152:153]
	v_pk_add_f32 v[138:139], v[138:139], v[154:155]
	v_cvt_pk_bf16_f32 v124, v152, v153
	v_cvt_pk_bf16_f32 v125, v154, v155
	v_pk_mul_f32 v[156:157], v[156:157], s[72:73]
	v_pk_mul_f32 v[158:159], v[158:159], s[72:73]
	v_exp_f32_e32 v156, v156
	v_exp_f32_e32 v157, v157
	v_exp_f32_e32 v158, v158
	v_exp_f32_e32 v159, v159
	v_pk_add_f32 v[140:141], v[140:141], v[156:157]
	v_pk_add_f32 v[140:141], v[140:141], v[158:159]
	v_cvt_pk_bf16_f32 v196, v156, v157
	v_cvt_pk_bf16_f32 v197, v158, v159
	s_add_i32 s77, s40, 48
	s_cmp_lt_u32 s77, s44
	s_cselect_b32 s76, s70, s71
	v_min_f32_e32 v152, s76, v240
	v_min_f32_e32 v153, s76, v241
	v_min_f32_e32 v154, s76, v242
	v_min_f32_e32 v155, s76, v243
	v_min_f32_e32 v156, s76, v248
	v_min_f32_e32 v157, s76, v249
	v_min_f32_e32 v158, s76, v250
	v_min_f32_e32 v159, s76, v251
	s_waitcnt lgkmcnt(0)
	v_mfma_f32_16x16x32_bf16 v[248:251], v[212:215], v[56:59], 0
	v_mfma_f32_16x16x32_bf16 v[248:251], v[216:219], v[60:63], v[248:251]
	v_pk_mul_f32 v[152:153], v[152:153], s[72:73]
	v_pk_mul_f32 v[154:155], v[154:155], s[72:73]
	v_exp_f32_e32 v152, v152
	v_exp_f32_e32 v153, v153
	v_exp_f32_e32 v154, v154
	v_exp_f32_e32 v155, v155
	v_pk_add_f32 v[138:139], v[138:139], v[152:153]
	v_pk_add_f32 v[138:139], v[138:139], v[154:155]
	v_cvt_pk_bf16_f32 v126, v152, v153
	v_cvt_pk_bf16_f32 v127, v154, v155
	v_pk_mul_f32 v[156:157], v[156:157], s[72:73]
	v_pk_mul_f32 v[158:159], v[158:159], s[72:73]
	v_exp_f32_e32 v156, v156
	v_exp_f32_e32 v157, v157
	v_exp_f32_e32 v158, v158
	v_exp_f32_e32 v159, v159
	v_pk_add_f32 v[140:141], v[140:141], v[156:157]
	v_pk_add_f32 v[140:141], v[140:141], v[158:159]
	v_cvt_pk_bf16_f32 v198, v156, v157
	v_cvt_pk_bf16_f32 v199, v158, v159
	s_add_i32 s77, s40, 64
	s_cmp_lt_u32 s77, s44
	s_cselect_b32 s76, s70, s71
	v_min_f32_e32 v152, s76, v236
	v_min_f32_e32 v153, s76, v237
	v_min_f32_e32 v154, s76, v238
	v_min_f32_e32 v155, s76, v239
	v_min_f32_e32 v156, s76, v244
	v_min_f32_e32 v157, s76, v245
	v_min_f32_e32 v158, s76, v246
	v_min_f32_e32 v159, s76, v247
	v_pk_mul_f32 v[152:153], v[152:153], s[72:73]
	v_pk_mul_f32 v[154:155], v[154:155], s[72:73]
	v_exp_f32_e32 v152, v152
	v_exp_f32_e32 v153, v153
	v_exp_f32_e32 v154, v154
	v_exp_f32_e32 v155, v155
	v_cndmask_b32_e64 v152, 0, v152, s[62:63]
	v_cndmask_b32_e64 v153, 0, v153, s[64:65]
	v_cndmask_b32_e64 v154, 0, v154, s[66:67]
	v_cndmask_b32_e64 v155, 0, v155, s[68:69]
	v_pk_add_f32 v[138:139], v[138:139], v[152:153]
	v_pk_add_f32 v[138:139], v[138:139], v[154:155]
	v_cvt_pk_bf16_f32 v128, v152, v153
	v_cvt_pk_bf16_f32 v129, v154, v155
	v_pk_mul_f32 v[156:157], v[156:157], s[72:73]
	v_pk_mul_f32 v[158:159], v[158:159], s[72:73]
	v_exp_f32_e32 v156, v156
	v_exp_f32_e32 v157, v157
	v_exp_f32_e32 v158, v158
	v_exp_f32_e32 v159, v159
	v_pk_add_f32 v[140:141], v[140:141], v[156:157]
	v_pk_add_f32 v[140:141], v[140:141], v[158:159]
	v_cvt_pk_bf16_f32 v200, v156, v157
	v_cvt_pk_bf16_f32 v201, v158, v159
	s_add_i32 s77, s40, 80
	s_cmp_lt_u32 s77, s44
	s_cselect_b32 s76, s70, s71
	v_min_f32_e32 v156, s76, v248
	v_min_f32_e32 v157, s76, v249
	v_min_f32_e32 v158, s76, v250
	v_min_f32_e32 v159, s76, v251
	v_pk_mul_f32 v[156:157], v[156:157], s[72:73]
	v_pk_mul_f32 v[158:159], v[158:159], s[72:73]
	v_exp_f32_e32 v156, v156
	v_exp_f32_e32 v157, v157
	v_exp_f32_e32 v158, v158
	v_exp_f32_e32 v159, v159
	v_cndmask_b32_e64 v156, 0, v156, s[62:63]
	v_cndmask_b32_e64 v157, 0, v157, s[64:65]
	v_cndmask_b32_e64 v158, 0, v158, s[66:67]
	v_cndmask_b32_e64 v159, 0, v159, s[68:69]
	v_pk_add_f32 v[140:141], v[140:141], v[156:157]
	v_pk_add_f32 v[140:141], v[140:141], v[158:159]
	v_cvt_pk_bf16_f32 v202, v156, v157
	v_cvt_pk_bf16_f32 v203, v158, v159
	v_add_f32_e32 v132, v138, v139
	v_add_f32_e32 v133, v140, v141
	ds_bpermute_b32 v142, v167, v132
	s_waitcnt lgkmcnt(0)
	v_add_f32_e32 v132, v132, v142
	ds_bpermute_b32 v142, v168, v132
	s_waitcnt lgkmcnt(0)
	v_add_f32_e32 v132, v132, v142
	ds_bpermute_b32 v142, v167, v133
	s_waitcnt lgkmcnt(0)
	v_add_f32_e32 v133, v133, v142
	ds_bpermute_b32 v142, v168, v133
	s_waitcnt lgkmcnt(0)
	v_add_f32_e32 v133, v133, v142
	ds_read_b64_tr_b16 v[236:237], v151 offset:0
	ds_read_b64_tr_b16 v[238:239], v151 offset:2304
	ds_read_b64_tr_b16 v[240:241], v151 offset:32
	ds_read_b64_tr_b16 v[242:243], v151 offset:2336
	ds_read_b64_tr_b16 v[244:245], v151 offset:64
	ds_read_b64_tr_b16 v[246:247], v151 offset:2368
	ds_read_b64_tr_b16 v[248:249], v151 offset:96
	ds_read_b64_tr_b16 v[250:251], v151 offset:2400
	s_waitcnt lgkmcnt(0)
	v_mfma_f32_16x16x32_bf16 v[204:207], v[236:239], v[112:115], 0
	v_mfma_f32_16x16x32_bf16 v[208:211], v[240:243], v[112:115], 0
	v_mfma_f32_16x16x32_bf16 v[212:215], v[244:247], v[112:115], 0
	v_mfma_f32_16x16x32_bf16 v[216:219], v[248:251], v[112:115], 0
	v_mfma_f32_16x16x32_bf16 v[220:223], v[236:239], v[184:187], 0
	v_mfma_f32_16x16x32_bf16 v[224:227], v[240:243], v[184:187], 0
	v_mfma_f32_16x16x32_bf16 v[228:231], v[244:247], v[184:187], 0
	v_mfma_f32_16x16x32_bf16 v[232:235], v[248:251], v[184:187], 0
	s_nop 7
	ds_read_b64_tr_b16 v[236:237], v151 offset:4608
	ds_read_b64_tr_b16 v[238:239], v151 offset:6912
	ds_read_b64_tr_b16 v[240:241], v151 offset:4640
	ds_read_b64_tr_b16 v[242:243], v151 offset:6944
	ds_read_b64_tr_b16 v[244:245], v151 offset:4672
	ds_read_b64_tr_b16 v[246:247], v151 offset:6976
	ds_read_b64_tr_b16 v[248:249], v151 offset:4704
	ds_read_b64_tr_b16 v[250:251], v151 offset:7008
	s_waitcnt lgkmcnt(0)
	v_mfma_f32_16x16x32_bf16 v[204:207], v[236:239], v[116:119], v[204:207]
	v_mfma_f32_16x16x32_bf16 v[208:211], v[240:243], v[116:119], v[208:211]
	v_mfma_f32_16x16x32_bf16 v[212:215], v[244:247], v[116:119], v[212:215]
	v_mfma_f32_16x16x32_bf16 v[216:219], v[248:251], v[116:119], v[216:219]
	v_mfma_f32_16x16x32_bf16 v[220:223], v[236:239], v[188:191], v[220:223]
	v_mfma_f32_16x16x32_bf16 v[224:227], v[240:243], v[188:191], v[224:227]
	v_mfma_f32_16x16x32_bf16 v[228:231], v[244:247], v[188:191], v[228:231]
	v_mfma_f32_16x16x32_bf16 v[232:235], v[248:251], v[188:191], v[232:235]
	s_nop 7
	ds_read_b64_tr_b16 v[236:237], v151 offset:9216
	ds_read_b64_tr_b16 v[238:239], v151 offset:11520
	ds_read_b64_tr_b16 v[240:241], v151 offset:9248
	ds_read_b64_tr_b16 v[242:243], v151 offset:11552
	ds_read_b64_tr_b16 v[244:245], v151 offset:9280
	ds_read_b64_tr_b16 v[246:247], v151 offset:11584
	ds_read_b64_tr_b16 v[248:249], v151 offset:9312
	ds_read_b64_tr_b16 v[250:251], v151 offset:11616
	s_waitcnt lgkmcnt(0)
	v_mfma_f32_16x16x32_bf16 v[204:207], v[236:239], v[120:123], v[204:207]
	v_mfma_f32_16x16x32_bf16 v[208:211], v[240:243], v[120:123], v[208:211]
	v_mfma_f32_16x16x32_bf16 v[212:215], v[244:247], v[120:123], v[212:215]
	v_mfma_f32_16x16x32_bf16 v[216:219], v[248:251], v[120:123], v[216:219]
	v_mfma_f32_16x16x32_bf16 v[220:223], v[236:239], v[192:195], v[220:223]
	v_mfma_f32_16x16x32_bf16 v[224:227], v[240:243], v[192:195], v[224:227]
	v_mfma_f32_16x16x32_bf16 v[228:231], v[244:247], v[192:195], v[228:231]
	v_mfma_f32_16x16x32_bf16 v[232:235], v[248:251], v[192:195], v[232:235]
	s_nop 7
	ds_read_b64_tr_b16 v[236:237], v151 offset:13824
	ds_read_b64_tr_b16 v[238:239], v151 offset:16128
	ds_read_b64_tr_b16 v[240:241], v151 offset:13856
	ds_read_b64_tr_b16 v[242:243], v151 offset:16160
	ds_read_b64_tr_b16 v[244:245], v151 offset:13888
	ds_read_b64_tr_b16 v[246:247], v151 offset:16192
	ds_read_b64_tr_b16 v[248:249], v151 offset:13920
	ds_read_b64_tr_b16 v[250:251], v151 offset:16224
	s_waitcnt lgkmcnt(0)
	v_mfma_f32_16x16x32_bf16 v[204:207], v[236:239], v[124:127], v[204:207]
	v_mfma_f32_16x16x32_bf16 v[208:211], v[240:243], v[124:127], v[208:211]
	v_mfma_f32_16x16x32_bf16 v[212:215], v[244:247], v[124:127], v[212:215]
	v_mfma_f32_16x16x32_bf16 v[216:219], v[248:251], v[124:127], v[216:219]
	v_mfma_f32_16x16x32_bf16 v[220:223], v[236:239], v[196:199], v[220:223]
	v_mfma_f32_16x16x32_bf16 v[224:227], v[240:243], v[196:199], v[224:227]
	v_mfma_f32_16x16x32_bf16 v[228:231], v[244:247], v[196:199], v[228:231]
	v_mfma_f32_16x16x32_bf16 v[232:235], v[248:251], v[196:199], v[232:235]
	s_nop 7
	ds_read_b64_tr_b16 v[236:237], v151 offset:18432
	ds_read_b64_tr_b16 v[238:239], v151 offset:20736
	ds_read_b64_tr_b16 v[240:241], v151 offset:18464
	ds_read_b64_tr_b16 v[242:243], v151 offset:20768
	ds_read_b64_tr_b16 v[244:245], v151 offset:18496
	ds_read_b64_tr_b16 v[246:247], v151 offset:20800
	ds_read_b64_tr_b16 v[248:249], v151 offset:18528
	ds_read_b64_tr_b16 v[250:251], v151 offset:20832
	s_waitcnt lgkmcnt(0)
	v_mfma_f32_16x16x32_bf16 v[204:207], v[236:239], v[128:131], v[204:207]
	v_mfma_f32_16x16x32_bf16 v[208:211], v[240:243], v[128:131], v[208:211]
	v_mfma_f32_16x16x32_bf16 v[212:215], v[244:247], v[128:131], v[212:215]
	v_mfma_f32_16x16x32_bf16 v[216:219], v[248:251], v[128:131], v[216:219]
	v_mfma_f32_16x16x32_bf16 v[220:223], v[236:239], v[200:203], v[220:223]
	v_mfma_f32_16x16x32_bf16 v[224:227], v[240:243], v[200:203], v[224:227]
	v_mfma_f32_16x16x32_bf16 v[228:231], v[244:247], v[200:203], v[228:231]
	v_mfma_f32_16x16x32_bf16 v[232:235], v[248:251], v[200:203], v[232:235]
	s_barrier
	ds_write_b128 v173, v[204:207] offset:0
	ds_write_b128 v173, v[208:211] offset:64
	ds_write_b128 v173, v[212:215] offset:128
	ds_write_b128 v173, v[216:219] offset:192
	ds_write_b32 v174, v132 offset:0
	ds_write_b128 v173, v[220:223] offset:4624
	ds_write_b128 v173, v[224:227] offset:4688
	ds_write_b128 v173, v[228:231] offset:4752
	ds_write_b128 v173, v[232:235] offset:4816
	ds_write_b32 v174, v133 offset:64
	s_waitcnt lgkmcnt(0)
	s_barrier
	s_mov_b32 s40, s42
	s_mov_b32 s41, s43
	v_mov_b32_e32 v173, v176
	v_mov_b32_e32 v174, v177
	v_mov_b32_e32 v175, v178
	v_mov_b32_e32 v179, v183
	v_mov_b32_e32 v182, v252
	s_lshr_b32 s44, s33, 2
	s_lshr_b32 s42, s15, 4
	s_add_i32 s43, s0, 0
	v_subrev_u32_e32 v143, s80, v174
	v_lshl_add_u32 v143, v143, 5, v161
	v_add_u32_e32 v143, 0x1b500, v143
	ds_read_b128 v[48:51], v143
	ds_read_b128 v[52:55], v143 offset:64
	ds_read_b128 v[56:59], v143 offset:8192
	ds_read_b128 v[60:63], v143 offset:8256
	s_waitcnt vmcnt(12)
	s_waitcnt lgkmcnt(0)
	v_mov_b32_e32 v138, 0
	v_mov_b32_e32 v139, 0
	v_mov_b32_e32 v140, 0
	v_mov_b32_e32 v141, 0
	v_mfma_f32_16x16x32_bf16 v[236:239], v[0:3], v[48:51], 0
	v_mfma_f32_16x16x32_bf16 v[236:239], v[4:7], v[52:55], v[236:239]
	v_mfma_f32_16x16x32_bf16 v[240:243], v[8:11], v[48:51], 0
	v_mfma_f32_16x16x32_bf16 v[240:243], v[12:15], v[52:55], v[240:243]
	v_mfma_f32_16x16x32_bf16 v[248:251], v[8:11], v[56:59], 0
	v_mfma_f32_16x16x32_bf16 v[248:251], v[12:15], v[60:63], v[248:251]
	s_nop 7
	s_add_i32 s77, s40, -64
	s_cmp_lt_u32 s77, s44
	s_cselect_b32 s76, s70, s71
	v_min_f32_e32 v152, s76, v236
	v_min_f32_e32 v153, s76, v237
	v_min_f32_e32 v154, s76, v238
	v_min_f32_e32 v155, s76, v239
	v_mfma_f32_16x16x32_bf16 v[236:239], v[16:19], v[48:51], 0
	v_mfma_f32_16x16x32_bf16 v[236:239], v[20:23], v[52:55], v[236:239]
	v_mfma_f32_16x16x32_bf16 v[244:247], v[16:19], v[56:59], 0
	v_mfma_f32_16x16x32_bf16 v[244:247], v[20:23], v[60:63], v[244:247]
	v_add_u32_e32 v136, 24, v182
	v_med3_i32 v136, v136, 0, s38
	v_lshl_add_u32 v136, v136, 9, v179
	global_load_dwordx4 v[0:3], v136, s[24:25]
	global_load_dwordx4 v[4:7], v136, s[24:25] offset:64
	v_pk_mul_f32 v[152:153], v[152:153], s[72:73]
	v_pk_mul_f32 v[154:155], v[154:155], s[72:73]
	v_exp_f32_e32 v152, v152
	v_exp_f32_e32 v153, v153
	v_exp_f32_e32 v154, v154
	v_exp_f32_e32 v155, v155
	v_cndmask_b32_e64 v152, 0, v152, s[54:55]
	v_cndmask_b32_e64 v153, 0, v153, s[56:57]
	v_cndmask_b32_e64 v154, 0, v154, s[58:59]
	v_cndmask_b32_e64 v155, 0, v155, s[60:61]
	v_pk_add_f32 v[138:139], v[138:139], v[152:153]
	v_pk_add_f32 v[138:139], v[138:139], v[154:155]
	v_cvt_pk_bf16_f32 v112, v152, v153
	v_cvt_pk_bf16_f32 v113, v154, v155
	s_add_i32 s77, s40, -48
	s_cmp_lt_u32 s77, s44
	s_cselect_b32 s76, s70, s71
	v_min_f32_e32 v152, s76, v240
	v_min_f32_e32 v153, s76, v241
	v_min_f32_e32 v154, s76, v242
	v_min_f32_e32 v155, s76, v243
	v_min_f32_e32 v156, s76, v248
	v_min_f32_e32 v157, s76, v249
	v_min_f32_e32 v158, s76, v250
	v_min_f32_e32 v159, s76, v251
	v_mfma_f32_16x16x32_bf16 v[240:243], v[24:27], v[48:51], 0
	v_mfma_f32_16x16x32_bf16 v[240:243], v[28:31], v[52:55], v[240:243]
	v_mfma_f32_16x16x32_bf16 v[248:251], v[24:27], v[56:59], 0
	v_mfma_f32_16x16x32_bf16 v[248:251], v[28:31], v[60:63], v[248:251]
	v_add_u32_e32 v135, 28, v182
	v_med3_i32 v135, v135, 0, s38
	v_lshl_add_u32 v135, v135, 9, v179
	global_load_dwordx4 v[8:11], v135, s[24:25]
	global_load_dwordx4 v[12:15], v135, s[24:25] offset:64
	v_pk_mul_f32 v[152:153], v[152:153], s[72:73]
	v_pk_mul_f32 v[154:155], v[154:155], s[72:73]
	v_exp_f32_e32 v152, v152
	v_exp_f32_e32 v153, v153
	v_exp_f32_e32 v154, v154
	v_exp_f32_e32 v155, v155
	v_pk_add_f32 v[138:139], v[138:139], v[152:153]
	v_pk_add_f32 v[138:139], v[138:139], v[154:155]
	v_cvt_pk_bf16_f32 v114, v152, v153
	v_cvt_pk_bf16_f32 v115, v154, v155
	v_pk_mul_f32 v[156:157], v[156:157], s[72:73]
	v_pk_mul_f32 v[158:159], v[158:159], s[72:73]
	v_exp_f32_e32 v156, v156
	v_exp_f32_e32 v157, v157
	v_exp_f32_e32 v158, v158
	v_exp_f32_e32 v159, v159
	v_cndmask_b32_e64 v156, 0, v156, s[54:55]
	v_cndmask_b32_e64 v157, 0, v157, s[56:57]
	v_cndmask_b32_e64 v158, 0, v158, s[58:59]
	v_cndmask_b32_e64 v159, 0, v159, s[60:61]
	v_pk_add_f32 v[140:141], v[140:141], v[156:157]
	v_pk_add_f32 v[140:141], v[140:141], v[158:159]
	v_cvt_pk_bf16_f32 v186, v156, v157
	v_cvt_pk_bf16_f32 v187, v158, v159
	s_add_i32 s77, s40, -32
	s_cmp_lt_u32 s77, s44
	s_cselect_b32 s76, s70, s71
	v_min_f32_e32 v152, s76, v236
	v_min_f32_e32 v153, s76, v237
	v_min_f32_e32 v154, s76, v238
	v_min_f32_e32 v155, s76, v239
	v_min_f32_e32 v156, s76, v244
	v_min_f32_e32 v157, s76, v245
	v_min_f32_e32 v158, s76, v246
	v_min_f32_e32 v159, s76, v247
	v_mfma_f32_16x16x32_bf16 v[236:239], v[32:35], v[48:51], 0
	v_mfma_f32_16x16x32_bf16 v[236:239], v[36:39], v[52:55], v[236:239]
	v_mfma_f32_16x16x32_bf16 v[244:247], v[32:35], v[56:59], 0
	v_mfma_f32_16x16x32_bf16 v[244:247], v[36:39], v[60:63], v[244:247]
	v_add_u32_e32 v136, 32, v182
	v_med3_i32 v136, v136, 0, s38
	v_lshl_add_u32 v136, v136, 9, v179
	global_load_dwordx4 v[16:19], v136, s[24:25]
	global_load_dwordx4 v[20:23], v136, s[24:25] offset:64
	v_pk_mul_f32 v[152:153], v[152:153], s[72:73]
	v_pk_mul_f32 v[154:155], v[154:155], s[72:73]
	v_exp_f32_e32 v152, v152
	v_exp_f32_e32 v153, v153
	v_exp_f32_e32 v154, v154
	v_exp_f32_e32 v155, v155
	v_pk_add_f32 v[138:139], v[138:139], v[152:153]
	v_pk_add_f32 v[138:139], v[138:139], v[154:155]
	v_cvt_pk_bf16_f32 v116, v152, v153
	v_cvt_pk_bf16_f32 v117, v154, v155
	v_pk_mul_f32 v[156:157], v[156:157], s[72:73]
	v_pk_mul_f32 v[158:159], v[158:159], s[72:73]
	v_exp_f32_e32 v156, v156
	v_exp_f32_e32 v157, v157
	v_exp_f32_e32 v158, v158
	v_exp_f32_e32 v159, v159
	v_pk_add_f32 v[140:141], v[140:141], v[156:157]
	v_pk_add_f32 v[140:141], v[140:141], v[158:159]
	v_cvt_pk_bf16_f32 v188, v156, v157
	v_cvt_pk_bf16_f32 v189, v158, v159
	s_add_i32 s77, s40, -16
	s_cmp_lt_u32 s77, s44
	s_cselect_b32 s76, s70, s71
	v_min_f32_e32 v152, s76, v240
	v_min_f32_e32 v153, s76, v241
	v_min_f32_e32 v154, s76, v242
	v_min_f32_e32 v155, s76, v243
	v_min_f32_e32 v156, s76, v248
	v_min_f32_e32 v157, s76, v249
	v_min_f32_e32 v158, s76, v250
	v_min_f32_e32 v159, s76, v251
	v_mfma_f32_16x16x32_bf16 v[240:243], v[40:43], v[48:51], 0
	v_mfma_f32_16x16x32_bf16 v[240:243], v[44:47], v[52:55], v[240:243]
	v_mfma_f32_16x16x32_bf16 v[248:251], v[40:43], v[56:59], 0
	v_mfma_f32_16x16x32_bf16 v[248:251], v[44:47], v[60:63], v[248:251]
	v_add_u32_e32 v135, 36, v182
	v_med3_i32 v135, v135, 0, s38
	v_lshl_add_u32 v135, v135, 9, v179
	global_load_dwordx4 v[24:27], v135, s[24:25]
	global_load_dwordx4 v[28:31], v135, s[24:25] offset:64
	v_pk_mul_f32 v[152:153], v[152:153], s[72:73]
	v_pk_mul_f32 v[154:155], v[154:155], s[72:73]
	v_exp_f32_e32 v152, v152
	v_exp_f32_e32 v153, v153
	v_exp_f32_e32 v154, v154
	v_exp_f32_e32 v155, v155
	v_pk_add_f32 v[138:139], v[138:139], v[152:153]
	v_pk_add_f32 v[138:139], v[138:139], v[154:155]
	v_cvt_pk_bf16_f32 v118, v152, v153
	v_cvt_pk_bf16_f32 v119, v154, v155
	v_pk_mul_f32 v[156:157], v[156:157], s[72:73]
	v_pk_mul_f32 v[158:159], v[158:159], s[72:73]
	v_exp_f32_e32 v156, v156
	v_exp_f32_e32 v157, v157
	v_exp_f32_e32 v158, v158
	v_exp_f32_e32 v159, v159
	v_pk_add_f32 v[140:141], v[140:141], v[156:157]
	v_pk_add_f32 v[140:141], v[140:141], v[158:159]
	v_cvt_pk_bf16_f32 v190, v156, v157
	v_cvt_pk_bf16_f32 v191, v158, v159
	s_add_i32 s77, s40, 0
	s_cmp_lt_u32 s77, s44
	s_cselect_b32 s76, s70, s71
	v_min_f32_e32 v152, s76, v236
	v_min_f32_e32 v153, s76, v237
	v_min_f32_e32 v154, s76, v238
	v_min_f32_e32 v155, s76, v239
	v_min_f32_e32 v156, s76, v244
	v_min_f32_e32 v157, s76, v245
	v_min_f32_e32 v158, s76, v246
	v_min_f32_e32 v159, s76, v247
	s_waitcnt vmcnt(6)
	v_mfma_f32_16x16x32_bf16 v[236:239], v[0:3], v[48:51], 0
	v_mfma_f32_16x16x32_bf16 v[236:239], v[4:7], v[52:55], v[236:239]
	v_mfma_f32_16x16x32_bf16 v[244:247], v[0:3], v[56:59], 0
	v_mfma_f32_16x16x32_bf16 v[244:247], v[4:7], v[60:63], v[244:247]
	v_pk_mul_f32 v[152:153], v[152:153], s[72:73]
	v_pk_mul_f32 v[154:155], v[154:155], s[72:73]
	v_exp_f32_e32 v152, v152
	v_exp_f32_e32 v153, v153
	v_exp_f32_e32 v154, v154
	v_exp_f32_e32 v155, v155
	v_pk_add_f32 v[138:139], v[138:139], v[152:153]
	v_pk_add_f32 v[138:139], v[138:139], v[154:155]
	v_cvt_pk_bf16_f32 v120, v152, v153
	v_cvt_pk_bf16_f32 v121, v154, v155
	v_pk_mul_f32 v[156:157], v[156:157], s[72:73]
	v_pk_mul_f32 v[158:159], v[158:159], s[72:73]
	v_exp_f32_e32 v156, v156
	v_exp_f32_e32 v157, v157
	v_exp_f32_e32 v158, v158
	v_exp_f32_e32 v159, v159
	v_pk_add_f32 v[140:141], v[140:141], v[156:157]
	v_pk_add_f32 v[140:141], v[140:141], v[158:159]
	v_cvt_pk_bf16_f32 v192, v156, v157
	v_cvt_pk_bf16_f32 v193, v158, v159
	s_add_i32 s77, s40, 16
	s_cmp_lt_u32 s77, s44
	s_cselect_b32 s76, s70, s71
	v_min_f32_e32 v152, s76, v240
	v_min_f32_e32 v153, s76, v241
	v_min_f32_e32 v154, s76, v242
	v_min_f32_e32 v155, s76, v243
	v_min_f32_e32 v156, s76, v248
	v_min_f32_e32 v157, s76, v249
	v_min_f32_e32 v158, s76, v250
	v_min_f32_e32 v159, s76, v251
	s_waitcnt vmcnt(4)
	v_mfma_f32_16x16x32_bf16 v[240:243], v[8:11], v[48:51], 0
	v_mfma_f32_16x16x32_bf16 v[240:243], v[12:15], v[52:55], v[240:243]
	v_mfma_f32_16x16x32_bf16 v[248:251], v[8:11], v[56:59], 0
	v_mfma_f32_16x16x32_bf16 v[248:251], v[12:15], v[60:63], v[248:251]
	v_pk_mul_f32 v[152:153], v[152:153], s[72:73]
	v_pk_mul_f32 v[154:155], v[154:155], s[72:73]
	v_exp_f32_e32 v152, v152
	v_exp_f32_e32 v153, v153
	v_exp_f32_e32 v154, v154
	v_exp_f32_e32 v155, v155
	v_pk_add_f32 v[138:139], v[138:139], v[152:153]
	v_pk_add_f32 v[138:139], v[138:139], v[154:155]
	v_cvt_pk_bf16_f32 v122, v152, v153
	v_cvt_pk_bf16_f32 v123, v154, v155
	v_pk_mul_f32 v[156:157], v[156:157], s[72:73]
	v_pk_mul_f32 v[158:159], v[158:159], s[72:73]
	v_exp_f32_e32 v156, v156
	v_exp_f32_e32 v157, v157
	v_exp_f32_e32 v158, v158
	v_exp_f32_e32 v159, v159
	v_pk_add_f32 v[140:141], v[140:141], v[156:157]
	v_pk_add_f32 v[140:141], v[140:141], v[158:159]
	v_cvt_pk_bf16_f32 v194, v156, v157
	v_cvt_pk_bf16_f32 v195, v158, v159
	s_add_i32 s77, s40, 32
	s_cmp_lt_u32 s77, s44
	s_cselect_b32 s76, s70, s71
	v_min_f32_e32 v152, s76, v236
	v_min_f32_e32 v153, s76, v237
	v_min_f32_e32 v154, s76, v238
	v_min_f32_e32 v155, s76, v239
	v_min_f32_e32 v156, s76, v244
	v_min_f32_e32 v157, s76, v245
	v_min_f32_e32 v158, s76, v246
	v_min_f32_e32 v159, s76, v247
	s_waitcnt vmcnt(2)
	v_mfma_f32_16x16x32_bf16 v[236:239], v[16:19], v[48:51], 0
	v_mfma_f32_16x16x32_bf16 v[236:239], v[20:23], v[52:55], v[236:239]
	v_mfma_f32_16x16x32_bf16 v[244:247], v[16:19], v[56:59], 0
	v_mfma_f32_16x16x32_bf16 v[244:247], v[20:23], v[60:63], v[244:247]
	v_pk_mul_f32 v[152:153], v[152:153], s[72:73]
	v_pk_mul_f32 v[154:155], v[154:155], s[72:73]
	v_exp_f32_e32 v152, v152
	v_exp_f32_e32 v153, v153
	v_exp_f32_e32 v154, v154
	v_exp_f32_e32 v155, v155
	v_pk_add_f32 v[138:139], v[138:139], v[152:153]
	v_pk_add_f32 v[138:139], v[138:139], v[154:155]
	v_cvt_pk_bf16_f32 v124, v152, v153
	v_cvt_pk_bf16_f32 v125, v154, v155
	v_pk_mul_f32 v[156:157], v[156:157], s[72:73]
	v_pk_mul_f32 v[158:159], v[158:159], s[72:73]
	v_exp_f32_e32 v156, v156
	v_exp_f32_e32 v157, v157
	v_exp_f32_e32 v158, v158
	v_exp_f32_e32 v159, v159
	v_pk_add_f32 v[140:141], v[140:141], v[156:157]
	v_pk_add_f32 v[140:141], v[140:141], v[158:159]
	v_cvt_pk_bf16_f32 v196, v156, v157
	v_cvt_pk_bf16_f32 v197, v158, v159
	s_add_i32 s77, s40, 48
	s_cmp_lt_u32 s77, s44
	s_cselect_b32 s76, s70, s71
	v_min_f32_e32 v152, s76, v240
	v_min_f32_e32 v153, s76, v241
	v_min_f32_e32 v154, s76, v242
	v_min_f32_e32 v155, s76, v243
	v_min_f32_e32 v156, s76, v248
	v_min_f32_e32 v157, s76, v249
	v_min_f32_e32 v158, s76, v250
	v_min_f32_e32 v159, s76, v251
	s_waitcnt vmcnt(0)
	v_mfma_f32_16x16x32_bf16 v[248:251], v[24:27], v[56:59], 0
	v_mfma_f32_16x16x32_bf16 v[248:251], v[28:31], v[60:63], v[248:251]
	v_pk_mul_f32 v[152:153], v[152:153], s[72:73]
	v_pk_mul_f32 v[154:155], v[154:155], s[72:73]
	v_exp_f32_e32 v152, v152
	v_exp_f32_e32 v153, v153
	v_exp_f32_e32 v154, v154
	v_exp_f32_e32 v155, v155
	v_pk_add_f32 v[138:139], v[138:139], v[152:153]
	v_pk_add_f32 v[138:139], v[138:139], v[154:155]
	v_cvt_pk_bf16_f32 v126, v152, v153
	v_cvt_pk_bf16_f32 v127, v154, v155
	v_pk_mul_f32 v[156:157], v[156:157], s[72:73]
	v_pk_mul_f32 v[158:159], v[158:159], s[72:73]
	v_exp_f32_e32 v156, v156
	v_exp_f32_e32 v157, v157
	v_exp_f32_e32 v158, v158
	v_exp_f32_e32 v159, v159
	v_pk_add_f32 v[140:141], v[140:141], v[156:157]
	v_pk_add_f32 v[140:141], v[140:141], v[158:159]
	v_cvt_pk_bf16_f32 v198, v156, v157
	v_cvt_pk_bf16_f32 v199, v158, v159
	s_add_i32 s77, s40, 64
	s_cmp_lt_u32 s77, s44
	s_cselect_b32 s76, s70, s71
	v_min_f32_e32 v152, s76, v236
	v_min_f32_e32 v153, s76, v237
	v_min_f32_e32 v154, s76, v238
	v_min_f32_e32 v155, s76, v239
	v_min_f32_e32 v156, s76, v244
	v_min_f32_e32 v157, s76, v245
	v_min_f32_e32 v158, s76, v246
	v_min_f32_e32 v159, s76, v247
	v_pk_mul_f32 v[152:153], v[152:153], s[72:73]
	v_pk_mul_f32 v[154:155], v[154:155], s[72:73]
	v_exp_f32_e32 v152, v152
	v_exp_f32_e32 v153, v153
	v_exp_f32_e32 v154, v154
	v_exp_f32_e32 v155, v155
	v_cndmask_b32_e64 v152, 0, v152, s[62:63]
	v_cndmask_b32_e64 v153, 0, v153, s[64:65]
	v_cndmask_b32_e64 v154, 0, v154, s[66:67]
	v_cndmask_b32_e64 v155, 0, v155, s[68:69]
	v_pk_add_f32 v[138:139], v[138:139], v[152:153]
	v_pk_add_f32 v[138:139], v[138:139], v[154:155]
	v_cvt_pk_bf16_f32 v128, v152, v153
	v_cvt_pk_bf16_f32 v129, v154, v155
	v_pk_mul_f32 v[156:157], v[156:157], s[72:73]
	v_pk_mul_f32 v[158:159], v[158:159], s[72:73]
	v_exp_f32_e32 v156, v156
	v_exp_f32_e32 v157, v157
	v_exp_f32_e32 v158, v158
	v_exp_f32_e32 v159, v159
	v_pk_add_f32 v[140:141], v[140:141], v[156:157]
	v_pk_add_f32 v[140:141], v[140:141], v[158:159]
	v_cvt_pk_bf16_f32 v200, v156, v157
	v_cvt_pk_bf16_f32 v201, v158, v159
	s_add_i32 s77, s40, 80
	s_cmp_lt_u32 s77, s44
	s_cselect_b32 s76, s70, s71
	v_min_f32_e32 v156, s76, v248
	v_min_f32_e32 v157, s76, v249
	v_min_f32_e32 v158, s76, v250
	v_min_f32_e32 v159, s76, v251
	v_pk_mul_f32 v[156:157], v[156:157], s[72:73]
	v_pk_mul_f32 v[158:159], v[158:159], s[72:73]
	v_exp_f32_e32 v156, v156
	v_exp_f32_e32 v157, v157
	v_exp_f32_e32 v158, v158
	v_exp_f32_e32 v159, v159
	v_cndmask_b32_e64 v156, 0, v156, s[62:63]
	v_cndmask_b32_e64 v157, 0, v157, s[64:65]
	v_cndmask_b32_e64 v158, 0, v158, s[66:67]
	v_cndmask_b32_e64 v159, 0, v159, s[68:69]
	v_pk_add_f32 v[140:141], v[140:141], v[156:157]
	v_pk_add_f32 v[140:141], v[140:141], v[158:159]
	v_cvt_pk_bf16_f32 v202, v156, v157
	v_cvt_pk_bf16_f32 v203, v158, v159
	v_add_f32_e32 v132, v138, v139
	v_add_f32_e32 v133, v140, v141
	v_add_u32_e32 v134, s42, v160
	v_lshlrev_b32_e32 v134, 4, v134
	v_add_u32_e32 v134, s43, v134
	v_subrev_u32_e32 v135, s15, v134
	v_lshrrev_b32_e32 v136, 4, v135
	v_add_u32_e32 v136, v136, v135
	v_mad_u32_u24 v176, v136, s79, v161
	v_lshl_add_u32 v177, v135, 2, s80
	s_sub_i32 s2, s42, 64
	v_add_u32_e32 v178, s2, v169
	v_and_b32_e32 v135, 3, v134
	v_lshlrev_b32_e32 v135, s13, v135
	v_lshrrev_b32_e32 v136, 2, v134
	v_add_u32_e32 v135, v135, v136
	v_lshl_add_u32 v135, v135, 7, v161
	v_subrev_u32_e32 v134, 0x400, v134
	v_and_b32_e32 v137, 3, v134
	v_lshlrev_b32_e32 v137, s13, v137
	v_bfe_u32 v135, v134, 2, 2
	v_add_u32_e32 v137, v137, v135
	v_lshl_add_u32 v183, v137, 7, v161
	v_ashrrev_i32_e32 v252, 4, v134
	v_med3_i32 v136, v252, 0, s14
	v_lshl_add_u32 v136, v136, 9, v183
	global_load_dwordx4 v[0:3], v136, s[20:21]
	global_load_dwordx4 v[4:7], v136, s[20:21] offset:64
	v_add_u32_e32 v135, 16, v252
	v_med3_i32 v135, v135, 0, s14
	v_lshl_add_u32 v135, v135, 9, v183
	global_load_dwordx4 v[8:11], v135, s[20:21]
	global_load_dwordx4 v[12:15], v135, s[20:21] offset:64
	v_add_u32_e32 v136, 32, v252
	v_med3_i32 v136, v136, 0, s14
	v_lshl_add_u32 v136, v136, 9, v183
	global_load_dwordx4 v[16:19], v136, s[20:21]
	global_load_dwordx4 v[20:23], v136, s[20:21] offset:64
	v_add_u32_e32 v135, 48, v252
	v_med3_i32 v135, v135, 0, s14
	v_lshl_add_u32 v135, v135, 9, v183
	global_load_dwordx4 v[24:27], v135, s[20:21]
	global_load_dwordx4 v[28:31], v135, s[20:21] offset:64
	v_add_u32_e32 v136, 64, v252
	v_med3_i32 v136, v136, 0, s14
	v_lshl_add_u32 v136, v136, 9, v183
	global_load_dwordx4 v[32:35], v136, s[20:21]
	global_load_dwordx4 v[36:39], v136, s[20:21] offset:64
	v_add_u32_e32 v135, 0x50, v252
	v_med3_i32 v135, v135, 0, s14
	v_lshl_add_u32 v135, v135, 9, v183
	global_load_dwordx4 v[40:43], v135, s[20:21]
	global_load_dwordx4 v[44:47], v135, s[20:21] offset:64
	ds_bpermute_b32 v142, v167, v132
	s_waitcnt lgkmcnt(0)
	v_add_f32_e32 v132, v132, v142
	ds_bpermute_b32 v142, v168, v132
	s_waitcnt lgkmcnt(0)
	v_add_f32_e32 v132, v132, v142
	ds_bpermute_b32 v142, v167, v133
	s_waitcnt lgkmcnt(0)
	v_add_f32_e32 v133, v133, v142
	ds_bpermute_b32 v142, v168, v133
	s_waitcnt lgkmcnt(0)
	v_add_f32_e32 v133, v133, v142
	s_waitcnt vmcnt(12)
	ds_write_b128 v165, v[64:67]
	ds_write_b128 v165, v[68:71] offset:1152
	ds_write_b128 v165, v[72:75] offset:2304
	ds_write_b128 v165, v[76:79] offset:3456
	s_waitcnt lgkmcnt(0)
	ds_read_b64_tr_b16 v[236:237], v166
	ds_read_b64_tr_b16 v[238:239], v166 offset:2304
	ds_read_b64_tr_b16 v[240:241], v166 offset:32
	ds_read_b64_tr_b16 v[242:243], v166 offset:2336
	ds_read_b64_tr_b16 v[244:245], v166 offset:64
	ds_read_b64_tr_b16 v[246:247], v166 offset:2368
	ds_read_b64_tr_b16 v[248:249], v166 offset:96
	ds_read_b64_tr_b16 v[250:251], v166 offset:2400
	s_waitcnt lgkmcnt(0)
	s_lshl_b32 s2, s41, s39
	s_lshl_b32 s2, s2, 7
	s_add_u32 s74, s26, s2
	s_addc_u32 s75, s27, 0
	v_and_b32_e32 v139, 3, v164
	v_lshl_add_u32 v139, v139, 7, v162
	s_add_i32 s2, s40, 32
	v_add_u32_e32 v138, s2, v164
	v_ashrrev_i32_e32 v138, 2, v138
	v_med3_i32 v138, v138, 0, s38
	v_lshl_add_u32 v138, v138, 9, v139
	global_load_dwordx4 v[64:67], v138, s[74:75]
	s_add_i32 s2, s40, 40
	v_add_u32_e32 v138, s2, v164
	v_ashrrev_i32_e32 v138, 2, v138
	v_med3_i32 v138, v138, 0, s38
	v_lshl_add_u32 v138, v138, 9, v139
	global_load_dwordx4 v[68:71], v138, s[74:75]
	s_add_i32 s2, s40, 48
	v_add_u32_e32 v138, s2, v164
	v_ashrrev_i32_e32 v138, 2, v138
	v_med3_i32 v138, v138, 0, s38
	v_lshl_add_u32 v138, v138, 9, v139
	global_load_dwordx4 v[72:75], v138, s[74:75]
	s_add_i32 s2, s40, 56
	v_add_u32_e32 v138, s2, v164
	v_ashrrev_i32_e32 v138, 2, v138
	v_med3_i32 v138, v138, 0, s38
	v_lshl_add_u32 v138, v138, 9, v139
	global_load_dwordx4 v[76:79], v138, s[74:75]
	ds_write_b128 v165, v[80:83]
	ds_write_b128 v165, v[84:87] offset:1152
	ds_write_b128 v165, v[88:91] offset:2304
	ds_write_b128 v165, v[92:95] offset:3456
	v_mfma_f32_16x16x32_bf16 v[204:207], v[236:239], v[112:115], 0
	v_mfma_f32_16x16x32_bf16 v[208:211], v[240:243], v[112:115], 0
	v_mfma_f32_16x16x32_bf16 v[212:215], v[244:247], v[112:115], 0
	v_mfma_f32_16x16x32_bf16 v[216:219], v[248:251], v[112:115], 0
	v_mfma_f32_16x16x32_bf16 v[220:223], v[236:239], v[184:187], 0
	v_mfma_f32_16x16x32_bf16 v[224:227], v[240:243], v[184:187], 0
	v_mfma_f32_16x16x32_bf16 v[228:231], v[244:247], v[184:187], 0
	v_mfma_f32_16x16x32_bf16 v[232:235], v[248:251], v[184:187], 0
	s_waitcnt lgkmcnt(0)
	ds_read_b64_tr_b16 v[236:237], v166
	ds_read_b64_tr_b16 v[238:239], v166 offset:2304
	ds_read_b64_tr_b16 v[240:241], v166 offset:32
	ds_read_b64_tr_b16 v[242:243], v166 offset:2336
	ds_read_b64_tr_b16 v[244:245], v166 offset:64
	ds_read_b64_tr_b16 v[246:247], v166 offset:2368
	ds_read_b64_tr_b16 v[248:249], v166 offset:96
	ds_read_b64_tr_b16 v[250:251], v166 offset:2400
	s_waitcnt lgkmcnt(0)
	s_lshl_b32 s2, s41, s39
	s_lshl_b32 s2, s2, 7
	s_add_u32 s74, s26, s2
	s_addc_u32 s75, s27, 0
	v_and_b32_e32 v139, 3, v164
	v_lshl_add_u32 v139, v139, 7, v162
	s_add_i32 s2, s40, 64
	v_add_u32_e32 v138, s2, v164
	v_ashrrev_i32_e32 v138, 2, v138
	v_med3_i32 v138, v138, 0, s38
	v_lshl_add_u32 v138, v138, 9, v139
	global_load_dwordx4 v[80:83], v138, s[74:75]
	s_add_i32 s2, s40, 72
	v_add_u32_e32 v138, s2, v164
	v_ashrrev_i32_e32 v138, 2, v138
	v_med3_i32 v138, v138, 0, s38
	v_lshl_add_u32 v138, v138, 9, v139
	global_load_dwordx4 v[84:87], v138, s[74:75]
	s_add_i32 s2, s40, 80
	v_add_u32_e32 v138, s2, v164
	v_ashrrev_i32_e32 v138, 2, v138
	v_med3_i32 v138, v138, 0, s38
	v_lshl_add_u32 v138, v138, 9, v139
	global_load_dwordx4 v[88:91], v138, s[74:75]
	s_add_i32 s2, s40, 88
	v_add_u32_e32 v138, s2, v164
	v_ashrrev_i32_e32 v138, 2, v138
	v_med3_i32 v138, v138, 0, s38
	v_lshl_add_u32 v138, v138, 9, v139
	global_load_dwordx4 v[92:95], v138, s[74:75]
	ds_write_b128 v165, v[96:99]
	ds_write_b128 v165, v[100:103] offset:1152
	ds_write_b128 v165, v[104:107] offset:2304
	ds_write_b128 v165, v[108:111] offset:3456
	v_mfma_f32_16x16x32_bf16 v[204:207], v[236:239], v[116:119], v[204:207]
	v_mfma_f32_16x16x32_bf16 v[208:211], v[240:243], v[116:119], v[208:211]
	v_mfma_f32_16x16x32_bf16 v[212:215], v[244:247], v[116:119], v[212:215]
	v_mfma_f32_16x16x32_bf16 v[216:219], v[248:251], v[116:119], v[216:219]
	v_mfma_f32_16x16x32_bf16 v[220:223], v[236:239], v[188:191], v[220:223]
	v_mfma_f32_16x16x32_bf16 v[224:227], v[240:243], v[188:191], v[224:227]
	v_mfma_f32_16x16x32_bf16 v[228:231], v[244:247], v[188:191], v[228:231]
	v_mfma_f32_16x16x32_bf16 v[232:235], v[248:251], v[188:191], v[232:235]
	s_waitcnt lgkmcnt(0)
	ds_read_b64_tr_b16 v[236:237], v166
	ds_read_b64_tr_b16 v[238:239], v166 offset:2304
	ds_read_b64_tr_b16 v[240:241], v166 offset:32
	ds_read_b64_tr_b16 v[242:243], v166 offset:2336
	ds_read_b64_tr_b16 v[244:245], v166 offset:64
	ds_read_b64_tr_b16 v[246:247], v166 offset:2368
	ds_read_b64_tr_b16 v[248:249], v166 offset:96
	ds_read_b64_tr_b16 v[250:251], v166 offset:2400
	s_waitcnt lgkmcnt(0)
	s_waitcnt vmcnt(4)
	ds_write_b128 v165, v[64:67]
	ds_write_b128 v165, v[68:71] offset:1152
	ds_write_b128 v165, v[72:75] offset:2304
	ds_write_b128 v165, v[76:79] offset:3456
	v_mfma_f32_16x16x32_bf16 v[204:207], v[236:239], v[120:123], v[204:207]
	v_mfma_f32_16x16x32_bf16 v[208:211], v[240:243], v[120:123], v[208:211]
	v_mfma_f32_16x16x32_bf16 v[212:215], v[244:247], v[120:123], v[212:215]
	v_mfma_f32_16x16x32_bf16 v[216:219], v[248:251], v[120:123], v[216:219]
	v_mfma_f32_16x16x32_bf16 v[220:223], v[236:239], v[192:195], v[220:223]
	v_mfma_f32_16x16x32_bf16 v[224:227], v[240:243], v[192:195], v[224:227]
	v_mfma_f32_16x16x32_bf16 v[228:231], v[244:247], v[192:195], v[228:231]
	v_mfma_f32_16x16x32_bf16 v[232:235], v[248:251], v[192:195], v[232:235]
	s_waitcnt lgkmcnt(0)
	ds_read_b64_tr_b16 v[236:237], v166
	ds_read_b64_tr_b16 v[238:239], v166 offset:2304
	ds_read_b64_tr_b16 v[240:241], v166 offset:32
	ds_read_b64_tr_b16 v[242:243], v166 offset:2336
	ds_read_b64_tr_b16 v[244:245], v166 offset:64
	ds_read_b64_tr_b16 v[246:247], v166 offset:2368
	ds_read_b64_tr_b16 v[248:249], v166 offset:96
	ds_read_b64_tr_b16 v[250:251], v166 offset:2400
	s_waitcnt lgkmcnt(0)
	s_waitcnt vmcnt(0)
	ds_write_b128 v165, v[80:83]
	ds_write_b128 v165, v[84:87] offset:1152
	ds_write_b128 v165, v[88:91] offset:2304
	ds_write_b128 v165, v[92:95] offset:3456
	v_mfma_f32_16x16x32_bf16 v[204:207], v[236:239], v[124:127], v[204:207]
	v_mfma_f32_16x16x32_bf16 v[208:211], v[240:243], v[124:127], v[208:211]
	v_mfma_f32_16x16x32_bf16 v[212:215], v[244:247], v[124:127], v[212:215]
	v_mfma_f32_16x16x32_bf16 v[216:219], v[248:251], v[124:127], v[216:219]
	v_mfma_f32_16x16x32_bf16 v[220:223], v[236:239], v[196:199], v[220:223]
	v_mfma_f32_16x16x32_bf16 v[224:227], v[240:243], v[196:199], v[224:227]
	v_mfma_f32_16x16x32_bf16 v[228:231], v[244:247], v[196:199], v[228:231]
	v_mfma_f32_16x16x32_bf16 v[232:235], v[248:251], v[196:199], v[232:235]
	s_waitcnt lgkmcnt(0)
	ds_read_b64_tr_b16 v[236:237], v166
	ds_read_b64_tr_b16 v[238:239], v166 offset:2304
	ds_read_b64_tr_b16 v[240:241], v166 offset:32
	ds_read_b64_tr_b16 v[242:243], v166 offset:2336
	ds_read_b64_tr_b16 v[244:245], v166 offset:64
	ds_read_b64_tr_b16 v[246:247], v166 offset:2368
	ds_read_b64_tr_b16 v[248:249], v166 offset:96
	ds_read_b64_tr_b16 v[250:251], v166 offset:2400
	s_waitcnt lgkmcnt(0)
	v_mfma_f32_16x16x32_bf16 v[204:207], v[236:239], v[128:131], v[204:207]
	v_mfma_f32_16x16x32_bf16 v[208:211], v[240:243], v[128:131], v[208:211]
	v_mfma_f32_16x16x32_bf16 v[212:215], v[244:247], v[128:131], v[212:215]
	v_mfma_f32_16x16x32_bf16 v[216:219], v[248:251], v[128:131], v[216:219]
	v_mfma_f32_16x16x32_bf16 v[220:223], v[236:239], v[200:203], v[220:223]
	v_mfma_f32_16x16x32_bf16 v[224:227], v[240:243], v[200:203], v[224:227]
	v_mfma_f32_16x16x32_bf16 v[228:231], v[244:247], v[200:203], v[228:231]
	v_mfma_f32_16x16x32_bf16 v[232:235], v[248:251], v[200:203], v[232:235]
	s_and_b32 s2, s43, 3
	s_lshl_b32 s2, s2, s13
	s_lshr_b32 s3, s43, 2
	s_add_i32 s2, s2, s3
	s_lshl_b32 s2, s2, 7
	s_add_u32 s74, s22, s2
	s_addc_u32 s75, s23, 0
	s_add_i32 s2, s42, -64
	v_add_u32_e32 v138, s2, v164
	v_med3_i32 v138, v138, 0, s14
	v_lshl_add_u32 v138, v138, 9, v162
	global_load_dwordx4 v[64:67], v138, s[74:75]
	s_add_i32 s2, s42, -56
	v_add_u32_e32 v138, s2, v164
	v_med3_i32 v138, v138, 0, s14
	v_lshl_add_u32 v138, v138, 9, v162
	global_load_dwordx4 v[68:71], v138, s[74:75]
	s_add_i32 s2, s42, -48
	v_add_u32_e32 v138, s2, v164
	v_med3_i32 v138, v138, 0, s14
	v_lshl_add_u32 v138, v138, 9, v162
	global_load_dwordx4 v[72:75], v138, s[74:75]
	s_add_i32 s2, s42, -40
	v_add_u32_e32 v138, s2, v164
	v_med3_i32 v138, v138, 0, s14
	v_lshl_add_u32 v138, v138, 9, v162
	global_load_dwordx4 v[76:79], v138, s[74:75]
	s_and_b32 s2, s43, 3
	s_lshl_b32 s2, s2, s13
	s_lshr_b32 s3, s43, 2
	s_add_i32 s2, s2, s3
	s_lshl_b32 s2, s2, 7
	s_add_u32 s74, s22, s2
	s_addc_u32 s75, s23, 0
	s_add_i32 s2, s42, -32
	v_add_u32_e32 v138, s2, v164
	v_med3_i32 v138, v138, 0, s14
	v_lshl_add_u32 v138, v138, 9, v162
	global_load_dwordx4 v[80:83], v138, s[74:75]
	s_add_i32 s2, s42, -24
	v_add_u32_e32 v138, s2, v164
	v_med3_i32 v138, v138, 0, s14
	v_lshl_add_u32 v138, v138, 9, v162
	global_load_dwordx4 v[84:87], v138, s[74:75]
	s_add_i32 s2, s42, -16
	v_add_u32_e32 v138, s2, v164
	v_med3_i32 v138, v138, 0, s14
	v_lshl_add_u32 v138, v138, 9, v162
	global_load_dwordx4 v[88:91], v138, s[74:75]
	s_add_i32 s2, s42, -8
	v_add_u32_e32 v138, s2, v164
	v_med3_i32 v138, v138, 0, s14
	v_lshl_add_u32 v138, v138, 9, v162
	global_load_dwordx4 v[92:95], v138, s[74:75]
	s_and_b32 s2, s43, 3
	s_lshl_b32 s2, s2, s13
	s_lshr_b32 s3, s43, 2
	s_add_i32 s2, s2, s3
	s_lshl_b32 s2, s2, 7
	s_add_u32 s74, s22, s2
	s_addc_u32 s75, s23, 0
	s_add_i32 s2, s42, 0
	v_add_u32_e32 v138, s2, v164
	v_med3_i32 v138, v138, 0, s14
	v_lshl_add_u32 v138, v138, 9, v162
	global_load_dwordx4 v[96:99], v138, s[74:75]
	s_add_i32 s2, s42, 8
	v_add_u32_e32 v138, s2, v164
	v_med3_i32 v138, v138, 0, s14
	v_lshl_add_u32 v138, v138, 9, v162
	global_load_dwordx4 v[100:103], v138, s[74:75]
	s_add_i32 s2, s42, 16
	v_add_u32_e32 v138, s2, v164
	v_med3_i32 v138, v138, 0, s14
	v_lshl_add_u32 v138, v138, 9, v162
	global_load_dwordx4 v[104:107], v138, s[74:75]
	s_add_i32 s2, s42, 24
	v_add_u32_e32 v138, s2, v164
	v_med3_i32 v138, v138, 0, s14
	v_lshl_add_u32 v138, v138, 9, v162
	global_load_dwordx4 v[108:111], v138, s[74:75]
	ds_read_b128 v[236:239], v173 offset:0
	ds_read_b128 v[240:243], v173 offset:64
	ds_read_b128 v[244:247], v173 offset:128
	ds_read_b128 v[248:251], v173 offset:192
	ds_read_b32 v142, v174 offset:0
	s_waitcnt lgkmcnt(0)
	v_add_f32_e32 v204, v236, v204
	v_add_f32_e32 v205, v237, v205
	v_add_f32_e32 v206, v238, v206
	v_add_f32_e32 v207, v239, v207
	v_add_f32_e32 v208, v240, v208
	v_add_f32_e32 v209, v241, v209
	v_add_f32_e32 v210, v242, v210
	v_add_f32_e32 v211, v243, v211
	v_add_f32_e32 v212, v244, v212
	v_add_f32_e32 v213, v245, v213
	v_add_f32_e32 v214, v246, v214
	v_add_f32_e32 v215, v247, v215
	v_add_f32_e32 v216, v248, v216
	v_add_f32_e32 v217, v249, v217
	v_add_f32_e32 v218, v250, v218
	v_add_f32_e32 v219, v251, v219
	v_add_f32_e32 v132, v142, v132
	ds_write_b128 v173, v[204:207] offset:0
	ds_write_b128 v173, v[208:211] offset:64
	ds_write_b128 v173, v[212:215] offset:128
	ds_write_b128 v173, v[216:219] offset:192
	ds_write_b32 v174, v132 offset:0
	ds_read_b128 v[236:239], v173 offset:18496
	ds_read_b128 v[240:243], v173 offset:18560
	ds_read_b128 v[244:247], v173 offset:18624
	ds_read_b128 v[248:251], v173 offset:18688
	ds_read_b32 v142, v174 offset:256
	s_waitcnt lgkmcnt(0)
	v_add_f32_e32 v220, v236, v220
	v_add_f32_e32 v221, v237, v221
	v_add_f32_e32 v222, v238, v222
	v_add_f32_e32 v223, v239, v223
	v_add_f32_e32 v224, v240, v224
	v_add_f32_e32 v225, v241, v225
	v_add_f32_e32 v226, v242, v226
	v_add_f32_e32 v227, v243, v227
	v_add_f32_e32 v228, v244, v228
	v_add_f32_e32 v229, v245, v229
	v_add_f32_e32 v230, v246, v230
	v_add_f32_e32 v231, v247, v231
	v_add_f32_e32 v232, v248, v232
	v_add_f32_e32 v233, v249, v233
	v_add_f32_e32 v234, v250, v234
	v_add_f32_e32 v235, v251, v235
	v_add_f32_e32 v133, v142, v133
	ds_write_b128 v173, v[220:223] offset:18496
	ds_write_b128 v173, v[224:227] offset:18560
	ds_write_b128 v173, v[228:231] offset:18624
	ds_write_b128 v173, v[232:235] offset:18688
	ds_write_b32 v174, v133 offset:256
	s_waitcnt lgkmcnt(0)
	s_barrier
	s_mov_b32 s40, s42
	s_mov_b32 s41, s43
	v_mov_b32_e32 v173, v176
	v_mov_b32_e32 v174, v177
	v_mov_b32_e32 v175, v178
	v_mov_b32_e32 v179, v183
	v_mov_b32_e32 v182, v252
	s_lshr_b32 s44, s33, 4
	s_lshr_b32 s42, s15, 4
	s_add_i32 s43, s0, 8
	v_subrev_u32_e32 v143, s80, v174
	v_lshl_add_u32 v143, v143, 5, v161
	v_add_u32_e32 v143, 0x1b500, v143
	ds_read_b128 v[48:51], v143
	ds_read_b128 v[52:55], v143 offset:64
	s_waitcnt vmcnt(12)
	s_waitcnt lgkmcnt(0)
	v_mov_b32_e32 v138, 0
	v_mov_b32_e32 v139, 0
	v_mfma_f32_16x16x32_bf16 v[236:239], v[0:3], v[48:51], 0
	v_mfma_f32_16x16x32_bf16 v[236:239], v[4:7], v[52:55], v[236:239]
	v_mfma_f32_16x16x32_bf16 v[240:243], v[8:11], v[48:51], 0
	v_mfma_f32_16x16x32_bf16 v[240:243], v[12:15], v[52:55], v[240:243]
	s_nop 7
	s_add_i32 s77, s40, -64
	s_cmp_lt_u32 s77, s44
	s_cselect_b32 s76, s70, s71
	v_min_f32_e32 v152, s76, v236
	v_min_f32_e32 v153, s76, v237
	v_min_f32_e32 v154, s76, v238
	v_min_f32_e32 v155, s76, v239
	v_mfma_f32_16x16x32_bf16 v[236:239], v[16:19], v[48:51], 0
	v_mfma_f32_16x16x32_bf16 v[236:239], v[20:23], v[52:55], v[236:239]
	v_add_u32_e32 v136, 0x60, v182
	v_med3_i32 v136, v136, 0, s38
	v_lshl_add_u32 v136, v136, 9, v179
	global_load_dwordx4 v[0:3], v136, s[24:25]
	global_load_dwordx4 v[4:7], v136, s[24:25] offset:64
	v_pk_mul_f32 v[152:153], v[152:153], s[72:73]
	v_pk_mul_f32 v[154:155], v[154:155], s[72:73]
	v_exp_f32_e32 v152, v152
	v_exp_f32_e32 v153, v153
	v_exp_f32_e32 v154, v154
	v_exp_f32_e32 v155, v155
	v_cndmask_b32_e64 v152, 0, v152, s[54:55]
	v_cndmask_b32_e64 v153, 0, v153, s[56:57]
	v_cndmask_b32_e64 v154, 0, v154, s[58:59]
	v_cndmask_b32_e64 v155, 0, v155, s[60:61]
	v_pk_add_f32 v[138:139], v[138:139], v[152:153]
	v_pk_add_f32 v[138:139], v[138:139], v[154:155]
	v_cvt_pk_bf16_f32 v112, v152, v153
	v_cvt_pk_bf16_f32 v113, v154, v155
	s_add_i32 s77, s40, -48
	s_cmp_lt_u32 s77, s44
	s_cselect_b32 s76, s70, s71
	v_min_f32_e32 v152, s76, v240
	v_min_f32_e32 v153, s76, v241
	v_min_f32_e32 v154, s76, v242
	v_min_f32_e32 v155, s76, v243
	v_mfma_f32_16x16x32_bf16 v[240:243], v[24:27], v[48:51], 0
	v_mfma_f32_16x16x32_bf16 v[240:243], v[28:31], v[52:55], v[240:243]
	v_add_u32_e32 v135, 0x70, v182
	v_med3_i32 v135, v135, 0, s38
	v_lshl_add_u32 v135, v135, 9, v179
	global_load_dwordx4 v[8:11], v135, s[24:25]
	global_load_dwordx4 v[12:15], v135, s[24:25] offset:64
	v_pk_mul_f32 v[152:153], v[152:153], s[72:73]
	v_pk_mul_f32 v[154:155], v[154:155], s[72:73]
	v_exp_f32_e32 v152, v152
	v_exp_f32_e32 v153, v153
	v_exp_f32_e32 v154, v154
	v_exp_f32_e32 v155, v155
	v_pk_add_f32 v[138:139], v[138:139], v[152:153]
	v_pk_add_f32 v[138:139], v[138:139], v[154:155]
	v_cvt_pk_bf16_f32 v114, v152, v153
	v_cvt_pk_bf16_f32 v115, v154, v155
	s_add_i32 s77, s40, -32
	s_cmp_lt_u32 s77, s44
	s_cselect_b32 s76, s70, s71
	v_min_f32_e32 v152, s76, v236
	v_min_f32_e32 v153, s76, v237
	v_min_f32_e32 v154, s76, v238
	v_min_f32_e32 v155, s76, v239
	v_mfma_f32_16x16x32_bf16 v[236:239], v[32:35], v[48:51], 0
	v_mfma_f32_16x16x32_bf16 v[236:239], v[36:39], v[52:55], v[236:239]
	v_add_u32_e32 v136, 0x80, v182
	v_med3_i32 v136, v136, 0, s38
	v_lshl_add_u32 v136, v136, 9, v179
	global_load_dwordx4 v[16:19], v136, s[24:25]
	global_load_dwordx4 v[20:23], v136, s[24:25] offset:64
	v_pk_mul_f32 v[152:153], v[152:153], s[72:73]
	v_pk_mul_f32 v[154:155], v[154:155], s[72:73]
	v_exp_f32_e32 v152, v152
	v_exp_f32_e32 v153, v153
	v_exp_f32_e32 v154, v154
	v_exp_f32_e32 v155, v155
	v_pk_add_f32 v[138:139], v[138:139], v[152:153]
	v_pk_add_f32 v[138:139], v[138:139], v[154:155]
	v_cvt_pk_bf16_f32 v116, v152, v153
	v_cvt_pk_bf16_f32 v117, v154, v155
	s_add_i32 s77, s40, -16
	s_cmp_lt_u32 s77, s44
	s_cselect_b32 s76, s70, s71
	v_min_f32_e32 v152, s76, v240
	v_min_f32_e32 v153, s76, v241
	v_min_f32_e32 v154, s76, v242
	v_min_f32_e32 v155, s76, v243
	v_mfma_f32_16x16x32_bf16 v[240:243], v[40:43], v[48:51], 0
	v_mfma_f32_16x16x32_bf16 v[240:243], v[44:47], v[52:55], v[240:243]
	v_pk_mul_f32 v[152:153], v[152:153], s[72:73]
	v_pk_mul_f32 v[154:155], v[154:155], s[72:73]
	v_exp_f32_e32 v152, v152
	v_exp_f32_e32 v153, v153
	v_exp_f32_e32 v154, v154
	v_exp_f32_e32 v155, v155
	v_pk_add_f32 v[138:139], v[138:139], v[152:153]
	v_pk_add_f32 v[138:139], v[138:139], v[154:155]
	v_cvt_pk_bf16_f32 v118, v152, v153
	v_cvt_pk_bf16_f32 v119, v154, v155
	s_add_i32 s77, s40, 0
	s_cmp_lt_u32 s77, s44
	s_cselect_b32 s76, s70, s71
	v_min_f32_e32 v152, s76, v236
	v_min_f32_e32 v153, s76, v237
	v_min_f32_e32 v154, s76, v238
	v_min_f32_e32 v155, s76, v239
	s_waitcnt vmcnt(4)
	v_mfma_f32_16x16x32_bf16 v[236:239], v[0:3], v[48:51], 0
	v_mfma_f32_16x16x32_bf16 v[236:239], v[4:7], v[52:55], v[236:239]
	v_pk_mul_f32 v[152:153], v[152:153], s[72:73]
	v_pk_mul_f32 v[154:155], v[154:155], s[72:73]
	v_exp_f32_e32 v152, v152
	v_exp_f32_e32 v153, v153
	v_exp_f32_e32 v154, v154
	v_exp_f32_e32 v155, v155
	v_pk_add_f32 v[138:139], v[138:139], v[152:153]
	v_pk_add_f32 v[138:139], v[138:139], v[154:155]
	v_cvt_pk_bf16_f32 v120, v152, v153
	v_cvt_pk_bf16_f32 v121, v154, v155
	s_add_i32 s77, s40, 16
	s_cmp_lt_u32 s77, s44
	s_cselect_b32 s76, s70, s71
	v_min_f32_e32 v152, s76, v240
	v_min_f32_e32 v153, s76, v241
	v_min_f32_e32 v154, s76, v242
	v_min_f32_e32 v155, s76, v243
	s_waitcnt vmcnt(2)
	v_mfma_f32_16x16x32_bf16 v[240:243], v[8:11], v[48:51], 0
	v_mfma_f32_16x16x32_bf16 v[240:243], v[12:15], v[52:55], v[240:243]
	v_pk_mul_f32 v[152:153], v[152:153], s[72:73]
	v_pk_mul_f32 v[154:155], v[154:155], s[72:73]
	v_exp_f32_e32 v152, v152
	v_exp_f32_e32 v153, v153
	v_exp_f32_e32 v154, v154
	v_exp_f32_e32 v155, v155
	v_pk_add_f32 v[138:139], v[138:139], v[152:153]
	v_pk_add_f32 v[138:139], v[138:139], v[154:155]
	v_cvt_pk_bf16_f32 v122, v152, v153
	v_cvt_pk_bf16_f32 v123, v154, v155
	s_add_i32 s77, s40, 32
	s_cmp_lt_u32 s77, s44
	s_cselect_b32 s76, s70, s71
	v_min_f32_e32 v152, s76, v236
	v_min_f32_e32 v153, s76, v237
	v_min_f32_e32 v154, s76, v238
	v_min_f32_e32 v155, s76, v239
	s_waitcnt vmcnt(0)
	v_mfma_f32_16x16x32_bf16 v[236:239], v[16:19], v[48:51], 0
	v_mfma_f32_16x16x32_bf16 v[236:239], v[20:23], v[52:55], v[236:239]
	v_pk_mul_f32 v[152:153], v[152:153], s[72:73]
	v_pk_mul_f32 v[154:155], v[154:155], s[72:73]
	v_exp_f32_e32 v152, v152
	v_exp_f32_e32 v153, v153
	v_exp_f32_e32 v154, v154
	v_exp_f32_e32 v155, v155
	v_pk_add_f32 v[138:139], v[138:139], v[152:153]
	v_pk_add_f32 v[138:139], v[138:139], v[154:155]
	v_cvt_pk_bf16_f32 v124, v152, v153
	v_cvt_pk_bf16_f32 v125, v154, v155
	s_add_i32 s77, s40, 48
	s_cmp_lt_u32 s77, s44
	s_cselect_b32 s76, s70, s71
	v_min_f32_e32 v152, s76, v240
	v_min_f32_e32 v153, s76, v241
	v_min_f32_e32 v154, s76, v242
	v_min_f32_e32 v155, s76, v243
	v_pk_mul_f32 v[152:153], v[152:153], s[72:73]
	v_pk_mul_f32 v[154:155], v[154:155], s[72:73]
	v_exp_f32_e32 v152, v152
	v_exp_f32_e32 v153, v153
	v_exp_f32_e32 v154, v154
	v_exp_f32_e32 v155, v155
	v_pk_add_f32 v[138:139], v[138:139], v[152:153]
	v_pk_add_f32 v[138:139], v[138:139], v[154:155]
	v_cvt_pk_bf16_f32 v126, v152, v153
	v_cvt_pk_bf16_f32 v127, v154, v155
	s_add_i32 s77, s40, 64
	s_cmp_lt_u32 s77, s44
	s_cselect_b32 s76, s70, s71
	v_min_f32_e32 v152, s76, v236
	v_min_f32_e32 v153, s76, v237
	v_min_f32_e32 v154, s76, v238
	v_min_f32_e32 v155, s76, v239
	v_pk_mul_f32 v[152:153], v[152:153], s[72:73]
	v_pk_mul_f32 v[154:155], v[154:155], s[72:73]
	v_exp_f32_e32 v152, v152
	v_exp_f32_e32 v153, v153
	v_exp_f32_e32 v154, v154
	v_exp_f32_e32 v155, v155
	v_cndmask_b32_e64 v152, 0, v152, s[62:63]
	v_cndmask_b32_e64 v153, 0, v153, s[64:65]
	v_cndmask_b32_e64 v154, 0, v154, s[66:67]
	v_cndmask_b32_e64 v155, 0, v155, s[68:69]
	v_pk_add_f32 v[138:139], v[138:139], v[152:153]
	v_pk_add_f32 v[138:139], v[138:139], v[154:155]
	v_cvt_pk_bf16_f32 v128, v152, v153
	v_cvt_pk_bf16_f32 v129, v154, v155
	v_add_f32_e32 v132, v138, v139
	v_add_u32_e32 v134, s42, v160
	v_lshlrev_b32_e32 v134, 4, v134
	v_add_u32_e32 v134, s43, v134
	v_subrev_u32_e32 v135, s15, v134
	v_lshrrev_b32_e32 v136, 4, v135
	v_add_u32_e32 v136, v136, v135
	v_mad_u32_u24 v176, v136, s79, v161
	v_lshl_add_u32 v177, v135, 2, s80
	s_sub_i32 s2, s42, 64
	v_add_u32_e32 v178, s2, v169
	v_and_b32_e32 v135, 3, v134
	v_lshlrev_b32_e32 v135, s13, v135
	v_lshrrev_b32_e32 v136, 2, v134
	v_add_u32_e32 v135, v135, v136
	v_lshl_add_u32 v135, v135, 7, v161
	v_subrev_u32_e32 v134, 0x400, v134
	v_and_b32_e32 v137, 3, v134
	v_lshlrev_b32_e32 v137, s13, v137
	v_bfe_u32 v135, v134, 2, 2
	v_add_u32_e32 v137, v137, v135
	v_lshl_add_u32 v183, v137, 7, v161
	v_ashrrev_i32_e32 v252, 4, v134
	v_med3_i32 v136, v252, 0, s14
	v_lshl_add_u32 v136, v136, 9, v183
	global_load_dwordx4 v[0:3], v136, s[20:21]
	global_load_dwordx4 v[4:7], v136, s[20:21] offset:64
	v_add_u32_e32 v135, 16, v252
	v_med3_i32 v135, v135, 0, s14
	v_lshl_add_u32 v135, v135, 9, v183
	global_load_dwordx4 v[8:11], v135, s[20:21]
	global_load_dwordx4 v[12:15], v135, s[20:21] offset:64
	v_add_u32_e32 v136, 32, v252
	v_med3_i32 v136, v136, 0, s14
	v_lshl_add_u32 v136, v136, 9, v183
	global_load_dwordx4 v[16:19], v136, s[20:21]
	global_load_dwordx4 v[20:23], v136, s[20:21] offset:64
	v_add_u32_e32 v135, 48, v252
	v_med3_i32 v135, v135, 0, s14
	v_lshl_add_u32 v135, v135, 9, v183
	global_load_dwordx4 v[24:27], v135, s[20:21]
	global_load_dwordx4 v[28:31], v135, s[20:21] offset:64
	v_add_u32_e32 v136, 64, v252
	v_med3_i32 v136, v136, 0, s14
	v_lshl_add_u32 v136, v136, 9, v183
	global_load_dwordx4 v[32:35], v136, s[20:21]
	global_load_dwordx4 v[36:39], v136, s[20:21] offset:64
	v_add_u32_e32 v135, 0x50, v252
	v_med3_i32 v135, v135, 0, s14
	v_lshl_add_u32 v135, v135, 9, v183
	global_load_dwordx4 v[40:43], v135, s[20:21]
	global_load_dwordx4 v[44:47], v135, s[20:21] offset:64
	ds_bpermute_b32 v142, v167, v132
	s_waitcnt lgkmcnt(0)
	v_add_f32_e32 v132, v132, v142
	ds_bpermute_b32 v142, v168, v132
	s_waitcnt lgkmcnt(0)
	v_add_f32_e32 v132, v132, v142
	s_waitcnt vmcnt(12)
	ds_write_b128 v165, v[64:67]
	ds_write_b128 v165, v[68:71] offset:1152
	ds_write_b128 v165, v[72:75] offset:2304
	ds_write_b128 v165, v[76:79] offset:3456
	s_waitcnt lgkmcnt(0)
	ds_read_b64_tr_b16 v[236:237], v166
	ds_read_b64_tr_b16 v[238:239], v166 offset:2304
	ds_read_b64_tr_b16 v[240:241], v166 offset:32
	ds_read_b64_tr_b16 v[242:243], v166 offset:2336
	ds_read_b64_tr_b16 v[244:245], v166 offset:64
	ds_read_b64_tr_b16 v[246:247], v166 offset:2368
	ds_read_b64_tr_b16 v[248:249], v166 offset:96
	ds_read_b64_tr_b16 v[250:251], v166 offset:2400
	s_waitcnt lgkmcnt(0)
	s_and_b32 s2, s41, 3
	s_lshl_b32 s2, s2, s39
	s_lshr_b32 s3, s41, 2
	s_add_i32 s2, s2, s3
	s_lshl_b32 s2, s2, 7
	s_add_u32 s74, s26, s2
	s_addc_u32 s75, s27, 0
	s_add_i32 s2, s40, 32
	v_add_u32_e32 v138, s2, v164
	v_med3_i32 v138, v138, 0, s38
	v_lshl_add_u32 v138, v138, 9, v162
	global_load_dwordx4 v[64:67], v138, s[74:75]
	s_add_i32 s2, s40, 40
	v_add_u32_e32 v138, s2, v164
	v_med3_i32 v138, v138, 0, s38
	v_lshl_add_u32 v138, v138, 9, v162
	global_load_dwordx4 v[68:71], v138, s[74:75]
	s_add_i32 s2, s40, 48
	v_add_u32_e32 v138, s2, v164
	v_med3_i32 v138, v138, 0, s38
	v_lshl_add_u32 v138, v138, 9, v162
	global_load_dwordx4 v[72:75], v138, s[74:75]
	s_add_i32 s2, s40, 56
	v_add_u32_e32 v138, s2, v164
	v_med3_i32 v138, v138, 0, s38
	v_lshl_add_u32 v138, v138, 9, v162
	global_load_dwordx4 v[76:79], v138, s[74:75]
	ds_write_b128 v165, v[80:83]
	ds_write_b128 v165, v[84:87] offset:1152
	ds_write_b128 v165, v[88:91] offset:2304
	ds_write_b128 v165, v[92:95] offset:3456
	v_mfma_f32_16x16x32_bf16 v[204:207], v[236:239], v[112:115], 0
	v_mfma_f32_16x16x32_bf16 v[208:211], v[240:243], v[112:115], 0
	v_mfma_f32_16x16x32_bf16 v[212:215], v[244:247], v[112:115], 0
	v_mfma_f32_16x16x32_bf16 v[216:219], v[248:251], v[112:115], 0
	s_waitcnt lgkmcnt(0)
	ds_read_b64_tr_b16 v[236:237], v166
	ds_read_b64_tr_b16 v[238:239], v166 offset:2304
	ds_read_b64_tr_b16 v[240:241], v166 offset:32
	ds_read_b64_tr_b16 v[242:243], v166 offset:2336
	ds_read_b64_tr_b16 v[244:245], v166 offset:64
	ds_read_b64_tr_b16 v[246:247], v166 offset:2368
	ds_read_b64_tr_b16 v[248:249], v166 offset:96
	ds_read_b64_tr_b16 v[250:251], v166 offset:2400
	s_waitcnt lgkmcnt(0)
	s_and_b32 s2, s41, 3
	s_lshl_b32 s2, s2, s39
	s_lshr_b32 s3, s41, 2
	s_add_i32 s2, s2, s3
	s_lshl_b32 s2, s2, 7
	s_add_u32 s74, s26, s2
	s_addc_u32 s75, s27, 0
	s_add_i32 s2, s40, 64
	v_add_u32_e32 v138, s2, v164
	v_med3_i32 v138, v138, 0, s38
	v_lshl_add_u32 v138, v138, 9, v162
	global_load_dwordx4 v[80:83], v138, s[74:75]
	s_add_i32 s2, s40, 72
	v_add_u32_e32 v138, s2, v164
	v_med3_i32 v138, v138, 0, s38
	v_lshl_add_u32 v138, v138, 9, v162
	global_load_dwordx4 v[84:87], v138, s[74:75]
	ds_write_b128 v165, v[96:99]
	ds_write_b128 v165, v[100:103] offset:1152
	ds_write_b128 v165, v[104:107] offset:2304
	ds_write_b128 v165, v[108:111] offset:3456
	v_mfma_f32_16x16x32_bf16 v[204:207], v[236:239], v[116:119], v[204:207]
	v_mfma_f32_16x16x32_bf16 v[208:211], v[240:243], v[116:119], v[208:211]
	v_mfma_f32_16x16x32_bf16 v[212:215], v[244:247], v[116:119], v[212:215]
	v_mfma_f32_16x16x32_bf16 v[216:219], v[248:251], v[116:119], v[216:219]
	s_waitcnt lgkmcnt(0)
	ds_read_b64_tr_b16 v[236:237], v166
	ds_read_b64_tr_b16 v[238:239], v166 offset:2304
	ds_read_b64_tr_b16 v[240:241], v166 offset:32
	ds_read_b64_tr_b16 v[242:243], v166 offset:2336
	ds_read_b64_tr_b16 v[244:245], v166 offset:64
	ds_read_b64_tr_b16 v[246:247], v166 offset:2368
	ds_read_b64_tr_b16 v[248:249], v166 offset:96
	ds_read_b64_tr_b16 v[250:251], v166 offset:2400
	s_waitcnt lgkmcnt(0)
	s_waitcnt vmcnt(2)
	ds_write_b128 v165, v[64:67]
	ds_write_b128 v165, v[68:71] offset:1152
	ds_write_b128 v165, v[72:75] offset:2304
	ds_write_b128 v165, v[76:79] offset:3456
	v_mfma_f32_16x16x32_bf16 v[204:207], v[236:239], v[120:123], v[204:207]
	v_mfma_f32_16x16x32_bf16 v[208:211], v[240:243], v[120:123], v[208:211]
	v_mfma_f32_16x16x32_bf16 v[212:215], v[244:247], v[120:123], v[212:215]
	v_mfma_f32_16x16x32_bf16 v[216:219], v[248:251], v[120:123], v[216:219]
	s_waitcnt lgkmcnt(0)
	ds_read_b64_tr_b16 v[236:237], v166
	ds_read_b64_tr_b16 v[238:239], v166 offset:2304
	ds_read_b64_tr_b16 v[240:241], v166 offset:32
	ds_read_b64_tr_b16 v[242:243], v166 offset:2336
	ds_read_b64_tr_b16 v[244:245], v166 offset:64
	ds_read_b64_tr_b16 v[246:247], v166 offset:2368
	ds_read_b64_tr_b16 v[248:249], v166 offset:96
	ds_read_b64_tr_b16 v[250:251], v166 offset:2400
	s_waitcnt lgkmcnt(0)
	s_waitcnt vmcnt(0)
	ds_write_b128 v165, v[80:83]
	ds_write_b128 v165, v[84:87] offset:1152
	v_mfma_f32_16x16x32_bf16 v[204:207], v[236:239], v[124:127], v[204:207]
	v_mfma_f32_16x16x32_bf16 v[208:211], v[240:243], v[124:127], v[208:211]
	v_mfma_f32_16x16x32_bf16 v[212:215], v[244:247], v[124:127], v[212:215]
	v_mfma_f32_16x16x32_bf16 v[216:219], v[248:251], v[124:127], v[216:219]
	s_waitcnt lgkmcnt(0)
	ds_read_b64_tr_b16 v[236:237], v166
	ds_read_b64_tr_b16 v[238:239], v166 offset:2304
	ds_read_b64_tr_b16 v[240:241], v166 offset:32
	ds_read_b64_tr_b16 v[242:243], v166 offset:2336
	ds_read_b64_tr_b16 v[244:245], v166 offset:64
	ds_read_b64_tr_b16 v[246:247], v166 offset:2368
	ds_read_b64_tr_b16 v[248:249], v166 offset:96
	ds_read_b64_tr_b16 v[250:251], v166 offset:2400
	s_waitcnt lgkmcnt(0)
	v_mfma_f32_16x16x32_bf16 v[204:207], v[236:239], v[128:131], v[204:207]
	v_mfma_f32_16x16x32_bf16 v[208:211], v[240:243], v[128:131], v[208:211]
	v_mfma_f32_16x16x32_bf16 v[212:215], v[244:247], v[128:131], v[212:215]
	v_mfma_f32_16x16x32_bf16 v[216:219], v[248:251], v[128:131], v[216:219]
	s_and_b32 s2, s43, 3
	s_lshl_b32 s2, s2, s13
	s_lshr_b32 s3, s43, 2
	s_add_i32 s2, s2, s3
	s_lshl_b32 s2, s2, 7
	s_add_u32 s74, s22, s2
	s_addc_u32 s75, s23, 0
	s_add_i32 s2, s42, -64
	v_add_u32_e32 v138, s2, v164
	v_med3_i32 v138, v138, 0, s14
	v_lshl_add_u32 v138, v138, 9, v162
	global_load_dwordx4 v[64:67], v138, s[74:75]
	s_add_i32 s2, s42, -56
	v_add_u32_e32 v138, s2, v164
	v_med3_i32 v138, v138, 0, s14
	v_lshl_add_u32 v138, v138, 9, v162
	global_load_dwordx4 v[68:71], v138, s[74:75]
	s_add_i32 s2, s42, -48
	v_add_u32_e32 v138, s2, v164
	v_med3_i32 v138, v138, 0, s14
	v_lshl_add_u32 v138, v138, 9, v162
	global_load_dwordx4 v[72:75], v138, s[74:75]
	s_add_i32 s2, s42, -40
	v_add_u32_e32 v138, s2, v164
	v_med3_i32 v138, v138, 0, s14
	v_lshl_add_u32 v138, v138, 9, v162
	global_load_dwordx4 v[76:79], v138, s[74:75]
	s_and_b32 s2, s43, 3
	s_lshl_b32 s2, s2, s13
	s_lshr_b32 s3, s43, 2
	s_add_i32 s2, s2, s3
	s_lshl_b32 s2, s2, 7
	s_add_u32 s74, s22, s2
	s_addc_u32 s75, s23, 0
	s_add_i32 s2, s42, -32
	v_add_u32_e32 v138, s2, v164
	v_med3_i32 v138, v138, 0, s14
	v_lshl_add_u32 v138, v138, 9, v162
	global_load_dwordx4 v[80:83], v138, s[74:75]
	s_add_i32 s2, s42, -24
	v_add_u32_e32 v138, s2, v164
	v_med3_i32 v138, v138, 0, s14
	v_lshl_add_u32 v138, v138, 9, v162
	global_load_dwordx4 v[84:87], v138, s[74:75]
	s_add_i32 s2, s42, -16
	v_add_u32_e32 v138, s2, v164
	v_med3_i32 v138, v138, 0, s14
	v_lshl_add_u32 v138, v138, 9, v162
	global_load_dwordx4 v[88:91], v138, s[74:75]
	s_add_i32 s2, s42, -8
	v_add_u32_e32 v138, s2, v164
	v_med3_i32 v138, v138, 0, s14
	v_lshl_add_u32 v138, v138, 9, v162
	global_load_dwordx4 v[92:95], v138, s[74:75]
	s_and_b32 s2, s43, 3
	s_lshl_b32 s2, s2, s13
	s_lshr_b32 s3, s43, 2
	s_add_i32 s2, s2, s3
	s_lshl_b32 s2, s2, 7
	s_add_u32 s74, s22, s2
	s_addc_u32 s75, s23, 0
	s_add_i32 s2, s42, 0
	v_add_u32_e32 v138, s2, v164
	v_med3_i32 v138, v138, 0, s14
	v_lshl_add_u32 v138, v138, 9, v162
	global_load_dwordx4 v[96:99], v138, s[74:75]
	s_add_i32 s2, s42, 8
	v_add_u32_e32 v138, s2, v164
	v_med3_i32 v138, v138, 0, s14
	v_lshl_add_u32 v138, v138, 9, v162
	global_load_dwordx4 v[100:103], v138, s[74:75]
	s_add_i32 s2, s42, 16
	v_add_u32_e32 v138, s2, v164
	v_med3_i32 v138, v138, 0, s14
	v_lshl_add_u32 v138, v138, 9, v162
	global_load_dwordx4 v[104:107], v138, s[74:75]
	s_add_i32 s2, s42, 24
	v_add_u32_e32 v138, s2, v164
	v_med3_i32 v138, v138, 0, s14
	v_lshl_add_u32 v138, v138, 9, v162
	global_load_dwordx4 v[108:111], v138, s[74:75]
	ds_read_b128 v[236:239], v173 offset:0
	ds_read_b128 v[240:243], v173 offset:64
	ds_read_b128 v[244:247], v173 offset:128
	ds_read_b128 v[248:251], v173 offset:192
	ds_read_b32 v142, v174 offset:0
	s_waitcnt lgkmcnt(0)
	v_add_f32_e32 v204, v236, v204
	v_add_f32_e32 v205, v237, v205
	v_add_f32_e32 v206, v238, v206
	v_add_f32_e32 v207, v239, v207
	v_add_f32_e32 v208, v240, v208
	v_add_f32_e32 v209, v241, v209
	v_add_f32_e32 v210, v242, v210
	v_add_f32_e32 v211, v243, v211
	v_add_f32_e32 v212, v244, v212
	v_add_f32_e32 v213, v245, v213
	v_add_f32_e32 v214, v246, v214
	v_add_f32_e32 v215, v247, v215
	v_add_f32_e32 v216, v248, v216
	v_add_f32_e32 v217, v249, v217
	v_add_f32_e32 v218, v250, v218
	v_add_f32_e32 v219, v251, v219
	v_add_f32_e32 v132, v142, v132
	ds_write_b128 v173, v[204:207] offset:0
	ds_write_b128 v173, v[208:211] offset:64
	ds_write_b128 v173, v[212:215] offset:128
	ds_write_b128 v173, v[216:219] offset:192
	ds_write_b32 v174, v132 offset:0
	s_mov_b32 s40, s42
	s_mov_b32 s41, s43
	v_mov_b32_e32 v173, v176
	v_mov_b32_e32 v174, v177
	v_mov_b32_e32 v175, v178
	v_mov_b32_e32 v179, v183
	v_mov_b32_e32 v182, v252
	s_lshr_b32 s44, s33, 4
	s_add_i32 s45, s10, s8
	s_cmp_lt_u32 s45, 0x800
	s_cbranch_scc1 .Latt_newunit
	s_mov_b32 s37, 1
	s_branch .Latt_ud_done

.Latt_ud_done:
	s_lshl_b32 s2, s0, 5
	s_add_i32 s42, s15, s2
	s_mov_b32 s43, 0
	v_subrev_u32_e32 v143, s80, v174
	v_lshl_add_u32 v143, v143, 5, v161
	v_add_u32_e32 v143, 0x1b500, v143
	ds_read_b128 v[48:51], v143
	ds_read_b128 v[52:55], v143 offset:64
	s_waitcnt vmcnt(12)
	s_waitcnt lgkmcnt(0)
	v_mov_b32_e32 v138, 0
	v_mov_b32_e32 v139, 0
	v_mfma_f32_16x16x32_bf16 v[236:239], v[0:3], v[48:51], 0
	v_mfma_f32_16x16x32_bf16 v[236:239], v[4:7], v[52:55], v[236:239]
	v_mfma_f32_16x16x32_bf16 v[240:243], v[8:11], v[48:51], 0
	v_mfma_f32_16x16x32_bf16 v[240:243], v[12:15], v[52:55], v[240:243]
	s_nop 7
	s_add_i32 s77, s40, -64
	s_cmp_lt_u32 s77, s44
	s_cselect_b32 s76, s70, s71
	v_min_f32_e32 v152, s76, v236
	v_min_f32_e32 v153, s76, v237
	v_min_f32_e32 v154, s76, v238
	v_min_f32_e32 v155, s76, v239
	v_mfma_f32_16x16x32_bf16 v[236:239], v[16:19], v[48:51], 0
	v_mfma_f32_16x16x32_bf16 v[236:239], v[20:23], v[52:55], v[236:239]
	v_add_u32_e32 v136, 0x60, v182
	v_med3_i32 v136, v136, 0, s38
	v_lshl_add_u32 v136, v136, 9, v179
	global_load_dwordx4 v[0:3], v136, s[24:25]
	global_load_dwordx4 v[4:7], v136, s[24:25] offset:64
	v_pk_mul_f32 v[152:153], v[152:153], s[72:73]
	v_pk_mul_f32 v[154:155], v[154:155], s[72:73]
	v_exp_f32_e32 v152, v152
	v_exp_f32_e32 v153, v153
	v_exp_f32_e32 v154, v154
	v_exp_f32_e32 v155, v155
	v_cndmask_b32_e64 v152, 0, v152, s[54:55]
	v_cndmask_b32_e64 v153, 0, v153, s[56:57]
	v_cndmask_b32_e64 v154, 0, v154, s[58:59]
	v_cndmask_b32_e64 v155, 0, v155, s[60:61]
	v_pk_add_f32 v[138:139], v[138:139], v[152:153]
	v_pk_add_f32 v[138:139], v[138:139], v[154:155]
	v_cvt_pk_bf16_f32 v112, v152, v153
	v_cvt_pk_bf16_f32 v113, v154, v155
	s_add_i32 s77, s40, -48
	s_cmp_lt_u32 s77, s44
	s_cselect_b32 s76, s70, s71
	v_min_f32_e32 v152, s76, v240
	v_min_f32_e32 v153, s76, v241
	v_min_f32_e32 v154, s76, v242
	v_min_f32_e32 v155, s76, v243
	v_mfma_f32_16x16x32_bf16 v[240:243], v[24:27], v[48:51], 0
	v_mfma_f32_16x16x32_bf16 v[240:243], v[28:31], v[52:55], v[240:243]
	v_add_u32_e32 v135, 0x70, v182
	v_med3_i32 v135, v135, 0, s38
	v_lshl_add_u32 v135, v135, 9, v179
	global_load_dwordx4 v[8:11], v135, s[24:25]
	global_load_dwordx4 v[12:15], v135, s[24:25] offset:64
	v_pk_mul_f32 v[152:153], v[152:153], s[72:73]
	v_pk_mul_f32 v[154:155], v[154:155], s[72:73]
	v_exp_f32_e32 v152, v152
	v_exp_f32_e32 v153, v153
	v_exp_f32_e32 v154, v154
	v_exp_f32_e32 v155, v155
	v_pk_add_f32 v[138:139], v[138:139], v[152:153]
	v_pk_add_f32 v[138:139], v[138:139], v[154:155]
	v_cvt_pk_bf16_f32 v114, v152, v153
	v_cvt_pk_bf16_f32 v115, v154, v155
	s_add_i32 s77, s40, -32
	s_cmp_lt_u32 s77, s44
	s_cselect_b32 s76, s70, s71
	v_min_f32_e32 v152, s76, v236
	v_min_f32_e32 v153, s76, v237
	v_min_f32_e32 v154, s76, v238
	v_min_f32_e32 v155, s76, v239
	v_mfma_f32_16x16x32_bf16 v[236:239], v[32:35], v[48:51], 0
	v_mfma_f32_16x16x32_bf16 v[236:239], v[36:39], v[52:55], v[236:239]
	v_add_u32_e32 v136, 0x80, v182
	v_med3_i32 v136, v136, 0, s38
	v_lshl_add_u32 v136, v136, 9, v179
	global_load_dwordx4 v[16:19], v136, s[24:25]
	global_load_dwordx4 v[20:23], v136, s[24:25] offset:64
	v_pk_mul_f32 v[152:153], v[152:153], s[72:73]
	v_pk_mul_f32 v[154:155], v[154:155], s[72:73]
	v_exp_f32_e32 v152, v152
	v_exp_f32_e32 v153, v153
	v_exp_f32_e32 v154, v154
	v_exp_f32_e32 v155, v155
	v_pk_add_f32 v[138:139], v[138:139], v[152:153]
	v_pk_add_f32 v[138:139], v[138:139], v[154:155]
	v_cvt_pk_bf16_f32 v116, v152, v153
	v_cvt_pk_bf16_f32 v117, v154, v155
	s_add_i32 s77, s40, -16
	s_cmp_lt_u32 s77, s44
	s_cselect_b32 s76, s70, s71
	v_min_f32_e32 v152, s76, v240
	v_min_f32_e32 v153, s76, v241
	v_min_f32_e32 v154, s76, v242
	v_min_f32_e32 v155, s76, v243
	v_mfma_f32_16x16x32_bf16 v[240:243], v[40:43], v[48:51], 0
	v_mfma_f32_16x16x32_bf16 v[240:243], v[44:47], v[52:55], v[240:243]
	v_pk_mul_f32 v[152:153], v[152:153], s[72:73]
	v_pk_mul_f32 v[154:155], v[154:155], s[72:73]
	v_exp_f32_e32 v152, v152
	v_exp_f32_e32 v153, v153
	v_exp_f32_e32 v154, v154
	v_exp_f32_e32 v155, v155
	v_pk_add_f32 v[138:139], v[138:139], v[152:153]
	v_pk_add_f32 v[138:139], v[138:139], v[154:155]
	v_cvt_pk_bf16_f32 v118, v152, v153
	v_cvt_pk_bf16_f32 v119, v154, v155
	s_add_i32 s77, s40, 0
	s_cmp_lt_u32 s77, s44
	s_cselect_b32 s76, s70, s71
	v_min_f32_e32 v152, s76, v236
	v_min_f32_e32 v153, s76, v237
	v_min_f32_e32 v154, s76, v238
	v_min_f32_e32 v155, s76, v239
	s_waitcnt vmcnt(4)
	v_mfma_f32_16x16x32_bf16 v[236:239], v[0:3], v[48:51], 0
	v_mfma_f32_16x16x32_bf16 v[236:239], v[4:7], v[52:55], v[236:239]
	v_pk_mul_f32 v[152:153], v[152:153], s[72:73]
	v_pk_mul_f32 v[154:155], v[154:155], s[72:73]
	v_exp_f32_e32 v152, v152
	v_exp_f32_e32 v153, v153
	v_exp_f32_e32 v154, v154
	v_exp_f32_e32 v155, v155
	v_pk_add_f32 v[138:139], v[138:139], v[152:153]
	v_pk_add_f32 v[138:139], v[138:139], v[154:155]
	v_cvt_pk_bf16_f32 v120, v152, v153
	v_cvt_pk_bf16_f32 v121, v154, v155
	s_add_i32 s77, s40, 16
	s_cmp_lt_u32 s77, s44
	s_cselect_b32 s76, s70, s71
	v_min_f32_e32 v152, s76, v240
	v_min_f32_e32 v153, s76, v241
	v_min_f32_e32 v154, s76, v242
	v_min_f32_e32 v155, s76, v243
	s_waitcnt vmcnt(2)
	v_mfma_f32_16x16x32_bf16 v[240:243], v[8:11], v[48:51], 0
	v_mfma_f32_16x16x32_bf16 v[240:243], v[12:15], v[52:55], v[240:243]
	v_pk_mul_f32 v[152:153], v[152:153], s[72:73]
	v_pk_mul_f32 v[154:155], v[154:155], s[72:73]
	v_exp_f32_e32 v152, v152
	v_exp_f32_e32 v153, v153
	v_exp_f32_e32 v154, v154
	v_exp_f32_e32 v155, v155
	v_pk_add_f32 v[138:139], v[138:139], v[152:153]
	v_pk_add_f32 v[138:139], v[138:139], v[154:155]
	v_cvt_pk_bf16_f32 v122, v152, v153
	v_cvt_pk_bf16_f32 v123, v154, v155
	s_add_i32 s77, s40, 32
	s_cmp_lt_u32 s77, s44
	s_cselect_b32 s76, s70, s71
	v_min_f32_e32 v152, s76, v236
	v_min_f32_e32 v153, s76, v237
	v_min_f32_e32 v154, s76, v238
	v_min_f32_e32 v155, s76, v239
	s_waitcnt vmcnt(0)
	v_mfma_f32_16x16x32_bf16 v[236:239], v[16:19], v[48:51], 0
	v_mfma_f32_16x16x32_bf16 v[236:239], v[20:23], v[52:55], v[236:239]
	v_pk_mul_f32 v[152:153], v[152:153], s[72:73]
	v_pk_mul_f32 v[154:155], v[154:155], s[72:73]
	v_exp_f32_e32 v152, v152
	v_exp_f32_e32 v153, v153
	v_exp_f32_e32 v154, v154
	v_exp_f32_e32 v155, v155
	v_pk_add_f32 v[138:139], v[138:139], v[152:153]
	v_pk_add_f32 v[138:139], v[138:139], v[154:155]
	v_cvt_pk_bf16_f32 v124, v152, v153
	v_cvt_pk_bf16_f32 v125, v154, v155
	s_add_i32 s77, s40, 48
	s_cmp_lt_u32 s77, s44
	s_cselect_b32 s76, s70, s71
	v_min_f32_e32 v152, s76, v240
	v_min_f32_e32 v153, s76, v241
	v_min_f32_e32 v154, s76, v242
	v_min_f32_e32 v155, s76, v243
	v_pk_mul_f32 v[152:153], v[152:153], s[72:73]
	v_pk_mul_f32 v[154:155], v[154:155], s[72:73]
	v_exp_f32_e32 v152, v152
	v_exp_f32_e32 v153, v153
	v_exp_f32_e32 v154, v154
	v_exp_f32_e32 v155, v155
	v_pk_add_f32 v[138:139], v[138:139], v[152:153]
	v_pk_add_f32 v[138:139], v[138:139], v[154:155]
	v_cvt_pk_bf16_f32 v126, v152, v153
	v_cvt_pk_bf16_f32 v127, v154, v155
	s_add_i32 s77, s40, 64
	s_cmp_lt_u32 s77, s44
	s_cselect_b32 s76, s70, s71
	v_min_f32_e32 v152, s76, v236
	v_min_f32_e32 v153, s76, v237
	v_min_f32_e32 v154, s76, v238
	v_min_f32_e32 v155, s76, v239
	v_pk_mul_f32 v[152:153], v[152:153], s[72:73]
	v_pk_mul_f32 v[154:155], v[154:155], s[72:73]
	v_exp_f32_e32 v152, v152
	v_exp_f32_e32 v153, v153
	v_exp_f32_e32 v154, v154
	v_exp_f32_e32 v155, v155
	v_cndmask_b32_e64 v152, 0, v152, s[62:63]
	v_cndmask_b32_e64 v153, 0, v153, s[64:65]
	v_cndmask_b32_e64 v154, 0, v154, s[66:67]
	v_cndmask_b32_e64 v155, 0, v155, s[68:69]
	v_pk_add_f32 v[138:139], v[138:139], v[152:153]
	v_pk_add_f32 v[138:139], v[138:139], v[154:155]
	v_cvt_pk_bf16_f32 v128, v152, v153
	v_cvt_pk_bf16_f32 v129, v154, v155
	v_add_f32_e32 v132, v138, v139
	v_add_u32_e32 v134, s42, v160
	v_add_u32_e32 v134, s43, v134
	v_subrev_u32_e32 v135, s15, v134
	v_lshrrev_b32_e32 v136, 4, v135
	v_add_u32_e32 v136, v136, v135
	v_mad_u32_u24 v176, v136, s79, v161
	v_lshl_add_u32 v177, v135, 2, s80
	s_sub_i32 s2, s42, 64
	v_add_u32_e32 v178, s2, v169
	v_and_b32_e32 v135, 3, v134
	v_lshlrev_b32_e32 v135, s13, v135
	v_lshrrev_b32_e32 v136, 2, v134
	v_add_u32_e32 v135, v135, v136
	v_lshl_add_u32 v135, v135, 7, v161
	v_add_u32_e32 v137, 16, v134
	v_and_b32_e32 v135, 3, v137
	v_lshlrev_b32_e32 v135, s13, v135
	v_lshrrev_b32_e32 v136, 2, v137
	v_add_u32_e32 v135, v135, v136
	v_lshl_add_u32 v135, v135, 7, v161
	s_mul_i32 s2, s0, 48
	s_add_i32 s2, s2, s15
	s_add_i32 s2, s2, -64
	v_add_u32_e32 v138, s2, v164
	v_and_b32_e32 v139, 3, v138
	v_lshlrev_b32_e32 v139, s13, v139
	v_bfe_u32 v140, v138, 2, 2
	v_add_u32_e32 v139, v139, v140
	v_lshl_add_u32 v139, v139, 7, v162
	v_ashrrev_i32_e32 v138, 4, v138
	v_med3_i32 v138, v138, 0, s14
	v_lshl_add_u32 v138, v138, 9, v139
	global_load_dwordx4 v[0:3], v138, s[20:21]
	s_mul_i32 s2, s0, 48
	s_add_i32 s2, s2, s15
	s_add_i32 s2, s2, -56
	v_add_u32_e32 v138, s2, v164
	v_and_b32_e32 v139, 3, v138
	v_lshlrev_b32_e32 v139, s13, v139
	v_bfe_u32 v140, v138, 2, 2
	v_add_u32_e32 v139, v139, v140
	v_lshl_add_u32 v139, v139, 7, v162
	v_ashrrev_i32_e32 v138, 4, v138
	v_med3_i32 v138, v138, 0, s14
	v_lshl_add_u32 v138, v138, 9, v139
	global_load_dwordx4 v[4:7], v138, s[20:21]
	s_mul_i32 s2, s0, 48
	s_add_i32 s2, s2, s15
	s_add_i32 s2, s2, -48
	v_add_u32_e32 v138, s2, v164
	v_and_b32_e32 v139, 3, v138
	v_lshlrev_b32_e32 v139, s13, v139
	v_bfe_u32 v140, v138, 2, 2
	v_add_u32_e32 v139, v139, v140
	v_lshl_add_u32 v139, v139, 7, v162
	v_ashrrev_i32_e32 v138, 4, v138
	v_med3_i32 v138, v138, 0, s14
	v_lshl_add_u32 v138, v138, 9, v139
	global_load_dwordx4 v[8:11], v138, s[20:21]
	s_mul_i32 s2, s0, 48
	s_add_i32 s2, s2, s15
	s_add_i32 s2, s2, -40
	v_add_u32_e32 v138, s2, v164
	v_and_b32_e32 v139, 3, v138
	v_lshlrev_b32_e32 v139, s13, v139
	v_bfe_u32 v140, v138, 2, 2
	v_add_u32_e32 v139, v139, v140
	v_lshl_add_u32 v139, v139, 7, v162
	v_ashrrev_i32_e32 v138, 4, v138
	v_med3_i32 v138, v138, 0, s14
	v_lshl_add_u32 v138, v138, 9, v139
	global_load_dwordx4 v[12:15], v138, s[20:21]
	s_mul_i32 s2, s0, 48
	s_add_i32 s2, s2, s15
	s_add_i32 s2, s2, -32
	v_add_u32_e32 v138, s2, v164
	v_and_b32_e32 v139, 3, v138
	v_lshlrev_b32_e32 v139, s13, v139
	v_bfe_u32 v140, v138, 2, 2
	v_add_u32_e32 v139, v139, v140
	v_lshl_add_u32 v139, v139, 7, v162
	v_ashrrev_i32_e32 v138, 4, v138
	v_med3_i32 v138, v138, 0, s14
	v_lshl_add_u32 v138, v138, 9, v139
	global_load_dwordx4 v[16:19], v138, s[20:21]
	s_mul_i32 s2, s0, 48
	s_add_i32 s2, s2, s15
	s_add_i32 s2, s2, -24
	v_add_u32_e32 v138, s2, v164
	v_and_b32_e32 v139, 3, v138
	v_lshlrev_b32_e32 v139, s13, v139
	v_bfe_u32 v140, v138, 2, 2
	v_add_u32_e32 v139, v139, v140
	v_lshl_add_u32 v139, v139, 7, v162
	v_ashrrev_i32_e32 v138, 4, v138
	v_med3_i32 v138, v138, 0, s14
	v_lshl_add_u32 v138, v138, 9, v139
	global_load_dwordx4 v[20:23], v138, s[20:21]
	s_mul_i32 s2, s0, 48
	s_add_i32 s2, s2, s15
	s_add_i32 s2, s2, -64
	v_add_u32_e32 v138, s2, v164
	v_and_b32_e32 v139, 3, v138
	v_lshlrev_b32_e32 v139, s13, v139
	v_bfe_u32 v140, v138, 2, 2
	v_add_u32_e32 v139, v139, v140
	v_lshl_add_u32 v139, v139, 7, v162
	v_ashrrev_i32_e32 v138, 4, v138
	v_med3_i32 v138, v138, 0, s14
	v_lshl_add_u32 v138, v138, 9, v139
	global_load_dwordx4 v[24:27], v138, s[22:23]
	s_mul_i32 s2, s0, 48
	s_add_i32 s2, s2, s15
	s_add_i32 s2, s2, -56
	v_add_u32_e32 v138, s2, v164
	v_and_b32_e32 v139, 3, v138
	v_lshlrev_b32_e32 v139, s13, v139
	v_bfe_u32 v140, v138, 2, 2
	v_add_u32_e32 v139, v139, v140
	v_lshl_add_u32 v139, v139, 7, v162
	v_ashrrev_i32_e32 v138, 4, v138
	v_med3_i32 v138, v138, 0, s14
	v_lshl_add_u32 v138, v138, 9, v139
	global_load_dwordx4 v[28:31], v138, s[22:23]
	s_mul_i32 s2, s0, 48
	s_add_i32 s2, s2, s15
	s_add_i32 s2, s2, -48
	v_add_u32_e32 v138, s2, v164
	v_and_b32_e32 v139, 3, v138
	v_lshlrev_b32_e32 v139, s13, v139
	v_bfe_u32 v140, v138, 2, 2
	v_add_u32_e32 v139, v139, v140
	v_lshl_add_u32 v139, v139, 7, v162
	v_ashrrev_i32_e32 v138, 4, v138
	v_med3_i32 v138, v138, 0, s14
	v_lshl_add_u32 v138, v138, 9, v139
	global_load_dwordx4 v[32:35], v138, s[22:23]
	s_mul_i32 s2, s0, 48
	s_add_i32 s2, s2, s15
	s_add_i32 s2, s2, -40
	v_add_u32_e32 v138, s2, v164
	v_and_b32_e32 v139, 3, v138
	v_lshlrev_b32_e32 v139, s13, v139
	v_bfe_u32 v140, v138, 2, 2
	v_add_u32_e32 v139, v139, v140
	v_lshl_add_u32 v139, v139, 7, v162
	v_ashrrev_i32_e32 v138, 4, v138
	v_med3_i32 v138, v138, 0, s14
	v_lshl_add_u32 v138, v138, 9, v139
	global_load_dwordx4 v[36:39], v138, s[22:23]
	s_mul_i32 s2, s0, 48
	s_add_i32 s2, s2, s15
	s_add_i32 s2, s2, -32
	v_add_u32_e32 v138, s2, v164
	v_and_b32_e32 v139, 3, v138
	v_lshlrev_b32_e32 v139, s13, v139
	v_bfe_u32 v140, v138, 2, 2
	v_add_u32_e32 v139, v139, v140
	v_lshl_add_u32 v139, v139, 7, v162
	v_ashrrev_i32_e32 v138, 4, v138
	v_med3_i32 v138, v138, 0, s14
	v_lshl_add_u32 v138, v138, 9, v139
	global_load_dwordx4 v[40:43], v138, s[22:23]
	s_mul_i32 s2, s0, 48
	s_add_i32 s2, s2, s15
	s_add_i32 s2, s2, -24
	v_add_u32_e32 v138, s2, v164
	v_and_b32_e32 v139, 3, v138
	v_lshlrev_b32_e32 v139, s13, v139
	v_bfe_u32 v140, v138, 2, 2
	v_add_u32_e32 v139, v139, v140
	v_lshl_add_u32 v139, v139, 7, v162
	v_ashrrev_i32_e32 v138, 4, v138
	v_med3_i32 v138, v138, 0, s14
	v_lshl_add_u32 v138, v138, 9, v139
	global_load_dwordx4 v[44:47], v138, s[22:23]
	s_lshl_b32 s2, s0, 5
	s_add_i32 s2, s2, s15
	s_add_i32 s2, s2, 0
	v_add_u32_e32 v138, s2, v164
	v_and_b32_e32 v139, 3, v138
	v_lshlrev_b32_e32 v139, s13, v139
	v_lshrrev_b32_e32 v140, 2, v138
	v_add_u32_e32 v139, v139, v140
	v_lshl_add_u32 v139, v139, 7, v162
	global_load_dwordx4 v[48:51], v139, s[18:19]
	s_lshl_b32 s2, s0, 5
	s_add_i32 s2, s2, s15
	s_add_i32 s2, s2, 8
	v_add_u32_e32 v138, s2, v164
	v_and_b32_e32 v139, 3, v138
	v_lshlrev_b32_e32 v139, s13, v139
	v_lshrrev_b32_e32 v140, 2, v138
	v_add_u32_e32 v139, v139, v140
	v_lshl_add_u32 v139, v139, 7, v162
	global_load_dwordx4 v[52:55], v139, s[18:19]
	s_lshl_b32 s2, s0, 5
	s_add_i32 s2, s2, s15
	s_add_i32 s2, s2, 16
	v_add_u32_e32 v138, s2, v164
	v_and_b32_e32 v139, 3, v138
	v_lshlrev_b32_e32 v139, s13, v139
	v_lshrrev_b32_e32 v140, 2, v138
	v_add_u32_e32 v139, v139, v140
	v_lshl_add_u32 v139, v139, 7, v162
	global_load_dwordx4 v[56:59], v139, s[18:19]
	s_lshl_b32 s2, s0, 5
	s_add_i32 s2, s2, s15
	s_add_i32 s2, s2, 24
	v_add_u32_e32 v138, s2, v164
	v_and_b32_e32 v139, 3, v138
	v_lshlrev_b32_e32 v139, s13, v139
	v_lshrrev_b32_e32 v140, 2, v138
	v_add_u32_e32 v139, v139, v140
	v_lshl_add_u32 v139, v139, 7, v162
	global_load_dwordx4 v[60:63], v139, s[18:19]
	ds_bpermute_b32 v142, v167, v132
	s_waitcnt lgkmcnt(0)
	v_add_f32_e32 v132, v132, v142
	ds_bpermute_b32 v142, v168, v132
	s_waitcnt lgkmcnt(0)
	v_add_f32_e32 v132, v132, v142
	s_waitcnt vmcnt(16)
	ds_write_b128 v165, v[64:67]
	ds_write_b128 v165, v[68:71] offset:1152
	ds_write_b128 v165, v[72:75] offset:2304
	ds_write_b128 v165, v[76:79] offset:3456
	s_waitcnt lgkmcnt(0)
	ds_read_b64_tr_b16 v[236:237], v166
	ds_read_b64_tr_b16 v[238:239], v166 offset:2304
	ds_read_b64_tr_b16 v[240:241], v166 offset:32
	ds_read_b64_tr_b16 v[242:243], v166 offset:2336
	ds_read_b64_tr_b16 v[244:245], v166 offset:64
	ds_read_b64_tr_b16 v[246:247], v166 offset:2368
	ds_read_b64_tr_b16 v[248:249], v166 offset:96
	ds_read_b64_tr_b16 v[250:251], v166 offset:2400
	s_waitcnt lgkmcnt(0)
	s_and_b32 s2, s41, 3
	s_lshl_b32 s2, s2, s39
	s_lshr_b32 s3, s41, 2
	s_add_i32 s2, s2, s3
	s_lshl_b32 s2, s2, 7
	s_add_u32 s74, s26, s2
	s_addc_u32 s75, s27, 0
	s_add_i32 s2, s40, 32
	v_add_u32_e32 v138, s2, v164
	v_med3_i32 v138, v138, 0, s38
	v_lshl_add_u32 v138, v138, 9, v162
	global_load_dwordx4 v[64:67], v138, s[74:75]
	s_add_i32 s2, s40, 40
	v_add_u32_e32 v138, s2, v164
	v_med3_i32 v138, v138, 0, s38
	v_lshl_add_u32 v138, v138, 9, v162
	global_load_dwordx4 v[68:71], v138, s[74:75]
	s_add_i32 s2, s40, 48
	v_add_u32_e32 v138, s2, v164
	v_med3_i32 v138, v138, 0, s38
	v_lshl_add_u32 v138, v138, 9, v162
	global_load_dwordx4 v[72:75], v138, s[74:75]
	s_add_i32 s2, s40, 56
	v_add_u32_e32 v138, s2, v164
	v_med3_i32 v138, v138, 0, s38
	v_lshl_add_u32 v138, v138, 9, v162
	global_load_dwordx4 v[76:79], v138, s[74:75]
	ds_write_b128 v165, v[80:83]
	ds_write_b128 v165, v[84:87] offset:1152
	ds_write_b128 v165, v[88:91] offset:2304
	ds_write_b128 v165, v[92:95] offset:3456
	v_mfma_f32_16x16x32_bf16 v[204:207], v[236:239], v[112:115], 0
	v_mfma_f32_16x16x32_bf16 v[208:211], v[240:243], v[112:115], 0
	v_mfma_f32_16x16x32_bf16 v[212:215], v[244:247], v[112:115], 0
	v_mfma_f32_16x16x32_bf16 v[216:219], v[248:251], v[112:115], 0
	s_waitcnt lgkmcnt(0)
	ds_read_b64_tr_b16 v[236:237], v166
	ds_read_b64_tr_b16 v[238:239], v166 offset:2304
	ds_read_b64_tr_b16 v[240:241], v166 offset:32
	ds_read_b64_tr_b16 v[242:243], v166 offset:2336
	ds_read_b64_tr_b16 v[244:245], v166 offset:64
	ds_read_b64_tr_b16 v[246:247], v166 offset:2368
	ds_read_b64_tr_b16 v[248:249], v166 offset:96
	ds_read_b64_tr_b16 v[250:251], v166 offset:2400
	s_waitcnt lgkmcnt(0)
	s_and_b32 s2, s41, 3
	s_lshl_b32 s2, s2, s39
	s_lshr_b32 s3, s41, 2
	s_add_i32 s2, s2, s3
	s_lshl_b32 s2, s2, 7
	s_add_u32 s74, s26, s2
	s_addc_u32 s75, s27, 0
	s_add_i32 s2, s40, 64
	v_add_u32_e32 v138, s2, v164
	v_med3_i32 v138, v138, 0, s38
	v_lshl_add_u32 v138, v138, 9, v162
	global_load_dwordx4 v[80:83], v138, s[74:75]
	s_add_i32 s2, s40, 72
	v_add_u32_e32 v138, s2, v164
	v_med3_i32 v138, v138, 0, s38
	v_lshl_add_u32 v138, v138, 9, v162
	global_load_dwordx4 v[84:87], v138, s[74:75]
	ds_write_b128 v165, v[96:99]
	ds_write_b128 v165, v[100:103] offset:1152
	ds_write_b128 v165, v[104:107] offset:2304
	ds_write_b128 v165, v[108:111] offset:3456
	v_mfma_f32_16x16x32_bf16 v[204:207], v[236:239], v[116:119], v[204:207]
	v_mfma_f32_16x16x32_bf16 v[208:211], v[240:243], v[116:119], v[208:211]
	v_mfma_f32_16x16x32_bf16 v[212:215], v[244:247], v[116:119], v[212:215]
	v_mfma_f32_16x16x32_bf16 v[216:219], v[248:251], v[116:119], v[216:219]
	s_waitcnt lgkmcnt(0)
	ds_read_b64_tr_b16 v[236:237], v166
	ds_read_b64_tr_b16 v[238:239], v166 offset:2304
	ds_read_b64_tr_b16 v[240:241], v166 offset:32
	ds_read_b64_tr_b16 v[242:243], v166 offset:2336
	ds_read_b64_tr_b16 v[244:245], v166 offset:64
	ds_read_b64_tr_b16 v[246:247], v166 offset:2368
	ds_read_b64_tr_b16 v[248:249], v166 offset:96
	ds_read_b64_tr_b16 v[250:251], v166 offset:2400
	s_waitcnt lgkmcnt(0)
	s_waitcnt vmcnt(2)
	ds_write_b128 v165, v[64:67]
	ds_write_b128 v165, v[68:71] offset:1152
	ds_write_b128 v165, v[72:75] offset:2304
	ds_write_b128 v165, v[76:79] offset:3456
	v_mfma_f32_16x16x32_bf16 v[204:207], v[236:239], v[120:123], v[204:207]
	v_mfma_f32_16x16x32_bf16 v[208:211], v[240:243], v[120:123], v[208:211]
	v_mfma_f32_16x16x32_bf16 v[212:215], v[244:247], v[120:123], v[212:215]
	v_mfma_f32_16x16x32_bf16 v[216:219], v[248:251], v[120:123], v[216:219]
	s_waitcnt lgkmcnt(0)
	ds_read_b64_tr_b16 v[236:237], v166
	ds_read_b64_tr_b16 v[238:239], v166 offset:2304
	ds_read_b64_tr_b16 v[240:241], v166 offset:32
	ds_read_b64_tr_b16 v[242:243], v166 offset:2336
	ds_read_b64_tr_b16 v[244:245], v166 offset:64
	ds_read_b64_tr_b16 v[246:247], v166 offset:2368
	ds_read_b64_tr_b16 v[248:249], v166 offset:96
	ds_read_b64_tr_b16 v[250:251], v166 offset:2400
	s_waitcnt lgkmcnt(0)
	s_waitcnt vmcnt(0)
	ds_write_b128 v165, v[80:83]
	ds_write_b128 v165, v[84:87] offset:1152
	v_mfma_f32_16x16x32_bf16 v[204:207], v[236:239], v[124:127], v[204:207]
	v_mfma_f32_16x16x32_bf16 v[208:211], v[240:243], v[124:127], v[208:211]
	v_mfma_f32_16x16x32_bf16 v[212:215], v[244:247], v[124:127], v[212:215]
	v_mfma_f32_16x16x32_bf16 v[216:219], v[248:251], v[124:127], v[216:219]
	s_waitcnt lgkmcnt(0)
	ds_read_b64_tr_b16 v[236:237], v166
	ds_read_b64_tr_b16 v[238:239], v166 offset:2304
	ds_read_b64_tr_b16 v[240:241], v166 offset:32
	ds_read_b64_tr_b16 v[242:243], v166 offset:2336
	ds_read_b64_tr_b16 v[244:245], v166 offset:64
	ds_read_b64_tr_b16 v[246:247], v166 offset:2368
	ds_read_b64_tr_b16 v[248:249], v166 offset:96
	ds_read_b64_tr_b16 v[250:251], v166 offset:2400
	s_waitcnt lgkmcnt(0)
	v_mfma_f32_16x16x32_bf16 v[204:207], v[236:239], v[128:131], v[204:207]
	v_mfma_f32_16x16x32_bf16 v[208:211], v[240:243], v[128:131], v[208:211]
	v_mfma_f32_16x16x32_bf16 v[212:215], v[244:247], v[128:131], v[212:215]
	v_mfma_f32_16x16x32_bf16 v[216:219], v[248:251], v[128:131], v[216:219]
	ds_read_b128 v[236:239], v173 offset:0
	ds_read_b128 v[240:243], v173 offset:64
	ds_read_b128 v[244:247], v173 offset:128
	ds_read_b128 v[248:251], v173 offset:192
	ds_read_b32 v142, v174 offset:0
	s_waitcnt lgkmcnt(0)
	v_add_f32_e32 v204, v236, v204
	v_add_f32_e32 v205, v237, v205
	v_add_f32_e32 v206, v238, v206
	v_add_f32_e32 v207, v239, v207
	v_add_f32_e32 v208, v240, v208
	v_add_f32_e32 v209, v241, v209
	v_add_f32_e32 v210, v242, v210
	v_add_f32_e32 v211, v243, v211
	v_add_f32_e32 v212, v244, v212
	v_add_f32_e32 v213, v245, v213
	v_add_f32_e32 v214, v246, v214
	v_add_f32_e32 v215, v247, v215
	v_add_f32_e32 v216, v248, v216
	v_add_f32_e32 v217, v249, v217
	v_add_f32_e32 v218, v250, v218
	v_add_f32_e32 v219, v251, v219
	v_add_f32_e32 v132, v142, v132
	ds_write_b128 v173, v[204:207] offset:0
	ds_write_b128 v173, v[208:211] offset:64
	ds_write_b128 v173, v[212:215] offset:128
	ds_write_b128 v173, v[216:219] offset:192
	ds_write_b32 v174, v132 offset:0
	s_waitcnt lgkmcnt(0)
	s_barrier
	ds_read_b128 v[204:207], v170
	ds_read_b128 v[208:211], v170 offset:16
	ds_read_b128 v[212:215], v170 offset:32
	ds_read_b128 v[216:219], v170 offset:48
	ds_read_b128 v[220:223], v170 offset:64
	ds_read_b128 v[224:227], v170 offset:80
	ds_read_b128 v[228:231], v170 offset:96
	ds_read_b128 v[232:235], v170 offset:112
	ds_read_b32 v142, v171
	s_lshl_b32 s2, s35, 11
	s_lshl_b32 s3, s36, 7
	s_add_u32 s2, s2, s3
	s_add_u32 s90, s6, s2
	s_addc_u32 s91, s7, 0
	s_waitcnt lgkmcnt(0)
	v_div_scale_f32 v143, s[30:31], v142, v142, 1.0
	v_rcp_f32_e32 v147, v143
	v_div_scale_f32 v134, vcc, 1.0, v142, 1.0
	v_fma_f32 v135, -v143, v147, 1.0
	v_fmac_f32_e32 v147, v135, v147
	v_mul_f32_e32 v135, v134, v147
	v_fma_f32 v136, -v143, v135, v134
	v_fmac_f32_e32 v135, v136, v147
	v_fma_f32 v143, -v143, v135, v134
	v_div_fmas_f32 v143, v143, v147, v135
	v_div_fixup_f32 v142, v143, v142, 1.0
	v_mul_f32_e32 v204, v142, v204
	v_mul_f32_e32 v205, v142, v205
	v_mul_f32_e32 v206, v142, v206
	v_mul_f32_e32 v207, v142, v207
	v_mul_f32_e32 v208, v142, v208
	v_mul_f32_e32 v209, v142, v209
	v_mul_f32_e32 v210, v142, v210
	v_mul_f32_e32 v211, v142, v211
	v_mul_f32_e32 v212, v142, v212
	v_mul_f32_e32 v213, v142, v213
	v_mul_f32_e32 v214, v142, v214
	v_mul_f32_e32 v215, v142, v215
	v_mul_f32_e32 v216, v142, v216
	v_mul_f32_e32 v217, v142, v217
	v_mul_f32_e32 v218, v142, v218
	v_mul_f32_e32 v219, v142, v219
	v_mul_f32_e32 v220, v142, v220
	v_mul_f32_e32 v221, v142, v221
	v_mul_f32_e32 v222, v142, v222
	v_mul_f32_e32 v223, v142, v223
	v_mul_f32_e32 v224, v142, v224
	v_mul_f32_e32 v225, v142, v225
	v_mul_f32_e32 v226, v142, v226
	v_mul_f32_e32 v227, v142, v227
	v_mul_f32_e32 v228, v142, v228
	v_mul_f32_e32 v229, v142, v229
	v_mul_f32_e32 v230, v142, v230
	v_mul_f32_e32 v231, v142, v231
	v_mul_f32_e32 v232, v142, v232
	v_mul_f32_e32 v233, v142, v233
	v_mul_f32_e32 v234, v142, v234
	v_mul_f32_e32 v235, v142, v235
	v_cvt_pk_bf16_f32 v112, v204, v205
	v_cvt_pk_bf16_f32 v113, v206, v207
	v_cvt_pk_bf16_f32 v114, v208, v209
	v_cvt_pk_bf16_f32 v115, v210, v211
	v_cvt_pk_bf16_f32 v116, v212, v213
	v_cvt_pk_bf16_f32 v117, v214, v215
	v_cvt_pk_bf16_f32 v118, v216, v217
	v_cvt_pk_bf16_f32 v119, v218, v219
	v_cvt_pk_bf16_f32 v120, v220, v221
	v_cvt_pk_bf16_f32 v121, v222, v223
	v_cvt_pk_bf16_f32 v122, v224, v225
	v_cvt_pk_bf16_f32 v123, v226, v227
	v_cvt_pk_bf16_f32 v124, v228, v229
	v_cvt_pk_bf16_f32 v125, v230, v231
	v_cvt_pk_bf16_f32 v126, v232, v233
	v_cvt_pk_bf16_f32 v127, v234, v235
	global_store_dwordx4 v172, v[112:115], s[90:91] nt
	global_store_dwordx4 v172, v[116:119], s[90:91] offset:16 nt
	global_store_dwordx4 v172, v[120:123], s[90:91] offset:32 nt
	global_store_dwordx4 v172, v[124:127], s[90:91] offset:48 nt
	s_barrier
	s_cmp_eq_u32 s37, 0
	s_cbranch_scc1 .Latt_unit
	s_waitcnt vmcnt(0)
	s_branch .LBB0_365
